# speedup vs baseline: 1.0136x; 1.0007x over previous
; #define LDA(dst, b, h) for (int m = 0; m < 4; ++m) for (int k = 0; k < 2; ++k) \
;     dst[m][k] = *reinterpret_cast<const bf16x8*>((char*)SA(b, h) + lds_byte(wr * 64 + m * 16 + fr, k * 32 + fq * 8))
; #define LDB(dst, b, h) for (int n = 0; n < 2; ++n) for (int k = 0; k < 2; ++k) \
;     dst[n][k] = *reinterpret_cast<const bf16x8*>((char*)SB(b, h) + lds_byte(wc * 32 + n * 16 + fr, k * 32 + fq * 8))
; #define MMA(ai, bj, At, Bt_) do { __builtin_amdgcn_s_setprio(1); \
;     for (int m = 0; m < 4; ++m) for (int n = 0; n < 2; ++n) for (int k = 0; k < 2; ++k) \
;       acc[ai][bj][m][n] = __builtin_amdgcn_mfma_f32_16x16x32_bf16(At[m][k], Bt_[n][k], acc[ai][bj][m][n], 0, 0, 0); \
;     __builtin_amdgcn_s_setprio(0); } while (0)
; #define WAIT_V(n) asm volatile("s_waitcnt vmcnt(" #n ")" ::: "memory")
; #define WAIT_L(n) asm volatile("s_waitcnt lgkmcnt(" #n ")" ::: "memory")
; #define BAR __builtin_amdgcn_s_barrier()
; #define SCHED __builtin_amdgcn_sched_barrier(0)
;     ...
;     for (int t = 0; t < nt - 2; t += 2) {
;       LDB(B0, 0, 0); SCHED; LDA(At, 0, 0); STAGE(SA(1, 1), A, brow + HALF, t + 1);
;       WAIT_L(8); BAR; WAIT_L(0); MMA(0, 0, At, B0); BAR; SCHED;
;       LDB(B1, 0, 1); STAGE(SB(0, 0), Bt, bcol, t + 2);
;       BAR; WAIT_L(0); MMA(0, 1, At, B1); BAR;
;       LDA(At, 0, 1); STAGE(SA(0, 0), A, brow, t + 2);
;       BAR; WAIT_L(0); MMA(1, 0, At, B0); BAR; SCHED;
;       STAGE(SB(0, 1), Bt, bcol + HALF, t + 2);
;       WAIT_V(6); BAR; MMA(1, 1, At, B1); BAR;
.LBB0_98:
	v_add_u32_e32 v143, s2, v142
	ds_read_b128 v[146:149], v143
	ds_read_b128 v[150:153], v143 offset:1024
	ds_read_b128 v[154:157], v143 offset:2048
	ds_read_b128 v[158:161], v143 offset:3072
	s_add_u32 s66, s55, s4
	s_addc_u32 s67, s57, s5
	s_add_i32 s63, s15, 0xc000
	ds_read_b128 v[162:165], v133
	ds_read_b128 v[184:187], v133 offset:1024
	ds_read_b128 v[188:191], v134
	ds_read_b128 v[192:195], v134 offset:1024
	ds_read_b128 v[196:199], v137
	ds_read_b128 v[200:203], v137 offset:1024
	ds_read_b128 v[204:207], v139
	ds_read_b128 v[208:211], v139 offset:1024
	s_mov_b32 m0, s63
	v_lshl_add_u64 v[144:145], s[66:67], 0, v[0:1]
	s_add_i32 s59, s15, 0xe000
	global_load_lds_dwordx4 v[144:145], off
	v_lshl_add_u64 v[144:145], s[66:67], 0, v[140:141]
	s_mov_b32 m0, s59
	s_nop 0
	global_load_lds_dwordx4 v[144:145], off
	s_waitcnt lgkmcnt(8)
	s_barrier
	s_waitcnt lgkmcnt(0)
	s_waitcnt lgkmcnt(0)
	v_mfma_f32_16x16x32_bf16 v[126:129], v[162:165], v[146:149], v[126:129]
	v_mfma_f32_16x16x32_bf16 v[122:125], v[162:165], v[154:157], v[122:125]
	v_mfma_f32_16x16x32_bf16 v[118:121], v[188:191], v[146:149], v[118:121]
	v_mfma_f32_16x16x32_bf16 v[114:117], v[188:191], v[154:157], v[114:117]
	v_mfma_f32_16x16x32_bf16 v[110:113], v[196:199], v[146:149], v[110:113]
	v_mfma_f32_16x16x32_bf16 v[106:109], v[196:199], v[154:157], v[106:109]
	v_mfma_f32_16x16x32_bf16 v[102:105], v[204:207], v[146:149], v[102:105]
	v_mfma_f32_16x16x32_bf16 v[98:101], v[204:207], v[154:157], v[98:101]
	v_mfma_f32_16x16x32_bf16 v[126:129], v[184:187], v[150:153], v[126:129]
	v_mfma_f32_16x16x32_bf16 v[122:125], v[184:187], v[158:161], v[122:125]
	v_mfma_f32_16x16x32_bf16 v[118:121], v[192:195], v[150:153], v[118:121]
	v_mfma_f32_16x16x32_bf16 v[114:117], v[192:195], v[158:161], v[114:117]
	v_mfma_f32_16x16x32_bf16 v[110:113], v[200:203], v[150:153], v[110:113]
	v_mfma_f32_16x16x32_bf16 v[106:109], v[200:203], v[158:161], v[106:109]
	v_mfma_f32_16x16x32_bf16 v[102:105], v[208:211], v[150:153], v[102:105]
	v_mfma_f32_16x16x32_bf16 v[98:101], v[208:211], v[158:161], v[98:101]
	s_barrier
	s_add_i32 s58, s58, 2
	s_add_u32 s65, s50, s4
	s_addc_u32 s70, s51, s5
	s_add_u32 s66, s65, 0x100
	v_add_u32_e32 v144, s76, v142
	s_addc_u32 s67, s70, 0
	s_mov_b32 m0, s16
	ds_read_b128 v[212:215], v144
	ds_read_b128 v[216:219], v144 offset:1024
	ds_read_b128 v[220:223], v144 offset:2048
	ds_read_b128 v[224:227], v144 offset:3072
	s_nop 0
	v_lshl_add_u64 v[166:167], s[66:67], 0, v[0:1]
	global_load_lds_dwordx4 v[166:167], off
	v_lshl_add_u64 v[166:167], s[66:67], 0, v[140:141]
	s_mov_b32 m0, s17
	s_nop 0
	global_load_lds_dwordx4 v[166:167], off
	s_barrier
	s_waitcnt lgkmcnt(0)
	s_waitcnt lgkmcnt(0)
	v_mfma_f32_16x16x32_bf16 v[94:97], v[162:165], v[212:215], v[94:97]
	v_mfma_f32_16x16x32_bf16 v[90:93], v[162:165], v[220:223], v[90:93]
	v_mfma_f32_16x16x32_bf16 v[86:89], v[188:191], v[212:215], v[86:89]
	v_mfma_f32_16x16x32_bf16 v[82:85], v[188:191], v[220:223], v[82:85]
	v_mfma_f32_16x16x32_bf16 v[78:81], v[196:199], v[212:215], v[78:81]
	v_mfma_f32_16x16x32_bf16 v[74:77], v[196:199], v[220:223], v[74:77]
	v_mfma_f32_16x16x32_bf16 v[70:73], v[204:207], v[212:215], v[70:73]
	v_mfma_f32_16x16x32_bf16 v[66:69], v[204:207], v[220:223], v[66:69]
	v_mfma_f32_16x16x32_bf16 v[94:97], v[184:187], v[216:219], v[94:97]
	v_mfma_f32_16x16x32_bf16 v[90:93], v[184:187], v[224:227], v[90:93]
	v_mfma_f32_16x16x32_bf16 v[86:89], v[192:195], v[216:219], v[86:89]
	v_mfma_f32_16x16x32_bf16 v[82:85], v[192:195], v[224:227], v[82:85]
	v_mfma_f32_16x16x32_bf16 v[78:81], v[200:203], v[216:219], v[78:81]
	v_mfma_f32_16x16x32_bf16 v[74:77], v[200:203], v[224:227], v[74:77]
	v_mfma_f32_16x16x32_bf16 v[70:73], v[208:211], v[216:219], v[70:73]
	v_mfma_f32_16x16x32_bf16 v[66:69], v[208:211], v[224:227], v[66:69]
	s_add_u32 s71, s44, s4
	s_addc_u32 s72, s45, s5
	s_add_u32 s66, s71, 0x100
	s_addc_u32 s67, s72, 0
	s_mov_b32 m0, s15
	s_barrier
	ds_read_b128 v[162:165], v133 offset:16384
	ds_read_b128 v[184:187], v133 offset:17408
	ds_read_b128 v[188:191], v134 offset:16384
	ds_read_b128 v[192:195], v134 offset:17408
	ds_read_b128 v[196:199], v137 offset:16384
	ds_read_b128 v[200:203], v137 offset:17408
	ds_read_b128 v[204:207], v139 offset:16384
	ds_read_b128 v[208:211], v139 offset:17408
	s_nop 0
	v_lshl_add_u64 v[166:167], s[66:67], 0, v[0:1]
	global_load_lds_dwordx4 v[166:167], off
	v_lshl_add_u64 v[166:167], s[66:67], 0, v[140:141]
	s_mov_b32 m0, s18
	s_nop 0
	global_load_lds_dwordx4 v[166:167], off
	s_barrier
	s_waitcnt lgkmcnt(0)
	s_waitcnt lgkmcnt(0)
	v_mfma_f32_16x16x32_bf16 v[62:65], v[162:165], v[146:149], v[62:65]
	v_mfma_f32_16x16x32_bf16 v[58:61], v[162:165], v[154:157], v[58:61]
	v_mfma_f32_16x16x32_bf16 v[54:57], v[188:191], v[146:149], v[54:57]
	v_mfma_f32_16x16x32_bf16 v[50:53], v[188:191], v[154:157], v[50:53]
	v_mfma_f32_16x16x32_bf16 v[46:49], v[196:199], v[146:149], v[46:49]
	v_mfma_f32_16x16x32_bf16 v[42:45], v[196:199], v[154:157], v[42:45]
	v_mfma_f32_16x16x32_bf16 v[38:41], v[204:207], v[146:149], v[38:41]
	v_mfma_f32_16x16x32_bf16 v[34:37], v[204:207], v[154:157], v[34:37]
	v_mfma_f32_16x16x32_bf16 v[62:65], v[184:187], v[150:153], v[62:65]
	v_mfma_f32_16x16x32_bf16 v[58:61], v[184:187], v[158:161], v[58:61]
	v_mfma_f32_16x16x32_bf16 v[54:57], v[192:195], v[150:153], v[54:57]
	v_mfma_f32_16x16x32_bf16 v[50:53], v[192:195], v[158:161], v[50:53]
	v_mfma_f32_16x16x32_bf16 v[46:49], v[200:203], v[150:153], v[46:49]
	v_mfma_f32_16x16x32_bf16 v[42:45], v[200:203], v[158:161], v[42:45]
	v_mfma_f32_16x16x32_bf16 v[38:41], v[208:211], v[150:153], v[38:41]
	v_mfma_f32_16x16x32_bf16 v[34:37], v[208:211], v[158:161], v[34:37]
	s_barrier
; #define LDA(dst, b, h) for (int m = 0; m < 4; ++m) for (int k = 0; k < 2; ++k) \
;     dst[m][k] = *reinterpret_cast<const bf16x8*>((char*)SA(b, h) + lds_byte(wr * 64 + m * 16 + fr, k * 32 + fq * 8))
; #define LDB(dst, b, h) for (int n = 0; n < 2; ++n) for (int k = 0; k < 2; ++k) \
;     dst[n][k] = *reinterpret_cast<const bf16x8*>((char*)SB(b, h) + lds_byte(wc * 32 + n * 16 + fr, k * 32 + fq * 8))
; #define MMA(ai, bj, At, Bt_) do { __builtin_amdgcn_s_setprio(1); \
;     for (int m = 0; m < 4; ++m) for (int n = 0; n < 2; ++n) for (int k = 0; k < 2; ++k) \
;       acc[ai][bj][m][n] = __builtin_amdgcn_mfma_f32_16x16x32_bf16(At[m][k], Bt_[n][k], acc[ai][bj][m][n], 0, 0, 0); \
;     __builtin_amdgcn_s_setprio(0); } while (0)
; #define WAIT_V(n) asm volatile("s_waitcnt vmcnt(" #n ")" ::: "memory")
; #define WAIT_L(n) asm volatile("s_waitcnt lgkmcnt(" #n ")" ::: "memory")
; #define BAR __builtin_amdgcn_s_barrier()
; #define SCHED __builtin_amdgcn_sched_barrier(0)
;     ...
;       STAGE(SB(0, 1), Bt, bcol + HALF, t + 2);
;       WAIT_V(6); BAR; MMA(1, 1, At, B1); BAR;
;       LDB(B0, 1, 0); SCHED; LDA(At, 1, 0); STAGE(SA(0, 1), A, brow + HALF, t + 2);
;       WAIT_L(8); BAR; WAIT_L(0); MMA(0, 0, At, B0); BAR; SCHED;
;       LDB(B1, 1, 1); STAGE(SB(1, 0), Bt, bcol, t + 3);
;       BAR; WAIT_L(0); MMA(0, 1, At, B1); BAR;
;       LDA(At, 1, 1); STAGE(SA(1, 0), A, brow, t + 3);
	s_add_u32 s73, s6, s4
	s_addc_u32 s82, s7, s5
	s_add_u32 s66, s73, 0x160100
	s_addc_u32 s67, s82, 0
	s_mov_b32 m0, s19
	s_nop 0
	v_lshl_add_u64 v[146:147], s[66:67], 0, v[0:1]
	global_load_lds_dwordx4 v[146:147], off
	v_lshl_add_u64 v[146:147], s[66:67], 0, v[140:141]
	s_mov_b32 m0, s21
	s_nop 0
	global_load_lds_dwordx4 v[146:147], off
	s_waitcnt vmcnt(6)
	s_barrier
	v_mfma_f32_16x16x32_bf16 v[30:33], v[162:165], v[212:215], v[30:33]
	v_mfma_f32_16x16x32_bf16 v[26:29], v[162:165], v[220:223], v[26:29]
	v_mfma_f32_16x16x32_bf16 v[22:25], v[188:191], v[212:215], v[22:25]
	v_mfma_f32_16x16x32_bf16 v[18:21], v[188:191], v[220:223], v[18:21]
	v_mfma_f32_16x16x32_bf16 v[14:17], v[196:199], v[212:215], v[14:17]
	v_mfma_f32_16x16x32_bf16 v[10:13], v[196:199], v[220:223], v[10:13]
	v_mfma_f32_16x16x32_bf16 v[6:9], v[204:207], v[212:215], v[6:9]
	v_mfma_f32_16x16x32_bf16 v[2:5], v[204:207], v[220:223], v[2:5]
	v_mfma_f32_16x16x32_bf16 v[30:33], v[184:187], v[216:219], v[30:33]
	v_mfma_f32_16x16x32_bf16 v[26:29], v[184:187], v[224:227], v[26:29]
	v_mfma_f32_16x16x32_bf16 v[22:25], v[192:195], v[216:219], v[22:25]
	v_mfma_f32_16x16x32_bf16 v[18:21], v[192:195], v[224:227], v[18:21]
	v_mfma_f32_16x16x32_bf16 v[14:17], v[200:203], v[216:219], v[14:17]
	v_mfma_f32_16x16x32_bf16 v[10:13], v[200:203], v[224:227], v[10:13]
	v_mfma_f32_16x16x32_bf16 v[6:9], v[208:211], v[216:219], v[6:9]
	v_mfma_f32_16x16x32_bf16 v[2:5], v[208:211], v[224:227], v[2:5]
	v_add_u32_e32 v145, s77, v142
	s_barrier
	ds_read_b128 v[148:151], v145
	ds_read_b128 v[152:155], v145 offset:1024
	ds_read_b128 v[156:159], v145 offset:2048
	ds_read_b128 v[160:163], v145 offset:3072
	s_add_u32 s66, s71, 0x160100
	s_addc_u32 s67, s72, 0
	s_mov_b32 m0, s30
	ds_read_b128 v[164:167], v133 offset:32768
	ds_read_b128 v[184:187], v133 offset:33792
	ds_read_b128 v[188:191], v134 offset:32768
	ds_read_b128 v[192:195], v134 offset:33792
	ds_read_b128 v[196:199], v137 offset:32768
	ds_read_b128 v[200:203], v137 offset:33792
	ds_read_b128 v[204:207], v139 offset:32768
	ds_read_b128 v[208:211], v139 offset:33792
	s_nop 0
	v_lshl_add_u64 v[146:147], s[66:67], 0, v[0:1]
	global_load_lds_dwordx4 v[146:147], off
	v_lshl_add_u64 v[146:147], s[66:67], 0, v[140:141]
	s_mov_b32 m0, s31
	s_nop 0
	global_load_lds_dwordx4 v[146:147], off
	s_waitcnt lgkmcnt(8)
	s_barrier
	s_waitcnt lgkmcnt(0)
	s_waitcnt lgkmcnt(0)
	v_mfma_f32_16x16x32_bf16 v[126:129], v[164:167], v[148:151], v[126:129]
	v_mfma_f32_16x16x32_bf16 v[122:125], v[164:167], v[156:159], v[122:125]
	v_mfma_f32_16x16x32_bf16 v[118:121], v[188:191], v[148:151], v[118:121]
	v_mfma_f32_16x16x32_bf16 v[114:117], v[188:191], v[156:159], v[114:117]
	v_mfma_f32_16x16x32_bf16 v[110:113], v[196:199], v[148:151], v[110:113]
	v_mfma_f32_16x16x32_bf16 v[106:109], v[196:199], v[156:159], v[106:109]
	v_mfma_f32_16x16x32_bf16 v[102:105], v[204:207], v[148:151], v[102:105]
	v_mfma_f32_16x16x32_bf16 v[98:101], v[204:207], v[156:159], v[98:101]
	v_mfma_f32_16x16x32_bf16 v[126:129], v[184:187], v[152:155], v[126:129]
	v_mfma_f32_16x16x32_bf16 v[122:125], v[184:187], v[160:163], v[122:125]
	v_mfma_f32_16x16x32_bf16 v[118:121], v[192:195], v[152:155], v[118:121]
	v_mfma_f32_16x16x32_bf16 v[114:117], v[192:195], v[160:163], v[114:117]
	v_mfma_f32_16x16x32_bf16 v[110:113], v[200:203], v[152:155], v[110:113]
	v_mfma_f32_16x16x32_bf16 v[106:109], v[200:203], v[160:163], v[106:109]
	v_mfma_f32_16x16x32_bf16 v[102:105], v[208:211], v[152:155], v[102:105]
	v_mfma_f32_16x16x32_bf16 v[98:101], v[208:211], v[160:163], v[98:101]
	s_barrier
	s_add_u32 s66, s65, 0x180
	v_add_u32_e32 v146, s78, v142
	s_addc_u32 s67, s70, 0
	s_mov_b32 m0, s34
	ds_read_b128 v[212:215], v146
	ds_read_b128 v[216:219], v146 offset:1024
	ds_read_b128 v[220:223], v146 offset:2048
	ds_read_b128 v[224:227], v146 offset:3072
	s_nop 0
	v_lshl_add_u64 v[228:229], s[66:67], 0, v[0:1]
	global_load_lds_dwordx4 v[228:229], off
	v_lshl_add_u64 v[228:229], s[66:67], 0, v[140:141]
	s_mov_b32 m0, s35
	s_nop 0
	global_load_lds_dwordx4 v[228:229], off
	s_barrier
	s_waitcnt lgkmcnt(0)
	s_waitcnt lgkmcnt(0)
	v_mfma_f32_16x16x32_bf16 v[94:97], v[164:167], v[212:215], v[94:97]
	v_mfma_f32_16x16x32_bf16 v[90:93], v[164:167], v[220:223], v[90:93]
	v_mfma_f32_16x16x32_bf16 v[86:89], v[188:191], v[212:215], v[86:89]
	v_mfma_f32_16x16x32_bf16 v[82:85], v[188:191], v[220:223], v[82:85]
	v_mfma_f32_16x16x32_bf16 v[78:81], v[196:199], v[212:215], v[78:81]
	v_mfma_f32_16x16x32_bf16 v[74:77], v[196:199], v[220:223], v[74:77]
	v_mfma_f32_16x16x32_bf16 v[70:73], v[204:207], v[212:215], v[70:73]
	v_mfma_f32_16x16x32_bf16 v[66:69], v[204:207], v[220:223], v[66:69]
	v_mfma_f32_16x16x32_bf16 v[94:97], v[184:187], v[216:219], v[94:97]
	v_mfma_f32_16x16x32_bf16 v[90:93], v[184:187], v[224:227], v[90:93]
	v_mfma_f32_16x16x32_bf16 v[86:89], v[192:195], v[216:219], v[86:89]
	v_mfma_f32_16x16x32_bf16 v[82:85], v[192:195], v[224:227], v[82:85]
	v_mfma_f32_16x16x32_bf16 v[78:81], v[200:203], v[216:219], v[78:81]
	v_mfma_f32_16x16x32_bf16 v[74:77], v[200:203], v[224:227], v[74:77]
	v_mfma_f32_16x16x32_bf16 v[70:73], v[208:211], v[216:219], v[70:73]
	v_mfma_f32_16x16x32_bf16 v[66:69], v[208:211], v[224:227], v[66:69]
	s_add_u32 s66, s71, 0x180
	s_addc_u32 s67, s72, 0
	s_mov_b32 m0, s37
	s_barrier
	ds_read_b128 v[164:167], v133 offset:49152
	ds_read_b128 v[184:187], v133 offset:50176
	ds_read_b128 v[188:191], v134 offset:49152
	ds_read_b128 v[192:195], v134 offset:50176
	ds_read_b128 v[196:199], v137 offset:49152
	ds_read_b128 v[200:203], v137 offset:50176
	ds_read_b128 v[204:207], v139 offset:49152
	ds_read_b128 v[208:211], v139 offset:50176
	s_nop 0
	v_lshl_add_u64 v[228:229], s[66:67], 0, v[0:1]
	global_load_lds_dwordx4 v[228:229], off
	v_lshl_add_u64 v[228:229], s[66:67], 0, v[140:141]
	s_mov_b32 m0, s38
	s_nop 0
	global_load_lds_dwordx4 v[228:229], off
	s_barrier
; #define LDA(dst, b, h) for (int m = 0; m < 4; ++m) for (int k = 0; k < 2; ++k) \
;     dst[m][k] = *reinterpret_cast<const bf16x8*>((char*)SA(b, h) + lds_byte(wr * 64 + m * 16 + fr, k * 32 + fq * 8))
; #define LDB(dst, b, h) for (int n = 0; n < 2; ++n) for (int k = 0; k < 2; ++k) \
;     dst[n][k] = *reinterpret_cast<const bf16x8*>((char*)SB(b, h) + lds_byte(wc * 32 + n * 16 + fr, k * 32 + fq * 8))
; #define MMA(ai, bj, At, Bt_) do { __builtin_amdgcn_s_setprio(1); \
;     for (int m = 0; m < 4; ++m) for (int n = 0; n < 2; ++n) for (int k = 0; k < 2; ++k) \
;       acc[ai][bj][m][n] = __builtin_amdgcn_mfma_f32_16x16x32_bf16(At[m][k], Bt_[n][k], acc[ai][bj][m][n], 0, 0, 0); \
;     __builtin_amdgcn_s_setprio(0); } while (0)
; #define WAIT_V(n) asm volatile("s_waitcnt vmcnt(" #n ")" ::: "memory")
; #define WAIT_L(n) asm volatile("s_waitcnt lgkmcnt(" #n ")" ::: "memory")
; #define BAR __builtin_amdgcn_s_barrier()
; #define SCHED __builtin_amdgcn_sched_barrier(0)
;     ...
;       BAR; WAIT_L(0); MMA(1, 0, At, B0); BAR; SCHED;
;       STAGE(SB(1, 1), Bt, bcol + HALF, t + 3);
;       WAIT_V(6); BAR; MMA(1, 1, At, B1); BAR;
;     }
;     { LDB(B0, 0, 0); LDA(At, 0, 0); STAGE(SA(1, 1), A, brow + HALF, nt - 1);
;       BAR; WAIT_L(0); MMA(0, 0, At, B0); BAR;
;       LDB(B1, 0, 1); BAR; WAIT_L(0); MMA(0, 1, At, B1); BAR;
	s_waitcnt lgkmcnt(0)
	s_waitcnt lgkmcnt(0)
	v_mfma_f32_16x16x32_bf16 v[62:65], v[164:167], v[148:151], v[62:65]
	v_mfma_f32_16x16x32_bf16 v[58:61], v[164:167], v[156:159], v[58:61]
	v_mfma_f32_16x16x32_bf16 v[54:57], v[188:191], v[148:151], v[54:57]
	v_mfma_f32_16x16x32_bf16 v[50:53], v[188:191], v[156:159], v[50:53]
	v_mfma_f32_16x16x32_bf16 v[46:49], v[196:199], v[148:151], v[46:49]
	v_mfma_f32_16x16x32_bf16 v[42:45], v[196:199], v[156:159], v[42:45]
	v_mfma_f32_16x16x32_bf16 v[38:41], v[204:207], v[148:151], v[38:41]
	v_mfma_f32_16x16x32_bf16 v[34:37], v[204:207], v[156:159], v[34:37]
	v_mfma_f32_16x16x32_bf16 v[62:65], v[184:187], v[152:155], v[62:65]
	v_mfma_f32_16x16x32_bf16 v[58:61], v[184:187], v[160:163], v[58:61]
	v_mfma_f32_16x16x32_bf16 v[54:57], v[192:195], v[152:155], v[54:57]
	v_mfma_f32_16x16x32_bf16 v[50:53], v[192:195], v[160:163], v[50:53]
	v_mfma_f32_16x16x32_bf16 v[46:49], v[200:203], v[152:155], v[46:49]
	v_mfma_f32_16x16x32_bf16 v[42:45], v[200:203], v[160:163], v[42:45]
	v_mfma_f32_16x16x32_bf16 v[38:41], v[208:211], v[152:155], v[38:41]
	v_mfma_f32_16x16x32_bf16 v[34:37], v[208:211], v[160:163], v[34:37]
	s_barrier
	s_add_u32 s66, s73, 0x160180
	s_addc_u32 s67, s82, 0
	s_mov_b32 m0, s41
	s_nop 0
	v_lshl_add_u64 v[148:149], s[66:67], 0, v[0:1]
	global_load_lds_dwordx4 v[148:149], off
	v_lshl_add_u64 v[148:149], s[66:67], 0, v[140:141]
	s_mov_b32 m0, s42
	s_nop 0
	global_load_lds_dwordx4 v[148:149], off
	s_waitcnt vmcnt(6)
	s_barrier
	v_mfma_f32_16x16x32_bf16 v[30:33], v[164:167], v[212:215], v[30:33]
	v_mfma_f32_16x16x32_bf16 v[26:29], v[164:167], v[220:223], v[26:29]
	v_mfma_f32_16x16x32_bf16 v[22:25], v[188:191], v[212:215], v[22:25]
	v_mfma_f32_16x16x32_bf16 v[18:21], v[188:191], v[220:223], v[18:21]
	v_mfma_f32_16x16x32_bf16 v[14:17], v[196:199], v[212:215], v[14:17]
	v_mfma_f32_16x16x32_bf16 v[10:13], v[196:199], v[220:223], v[10:13]
	v_mfma_f32_16x16x32_bf16 v[6:9], v[204:207], v[212:215], v[6:9]
	v_mfma_f32_16x16x32_bf16 v[2:5], v[204:207], v[220:223], v[2:5]
	v_mfma_f32_16x16x32_bf16 v[30:33], v[184:187], v[216:219], v[30:33]
	v_mfma_f32_16x16x32_bf16 v[26:29], v[184:187], v[224:227], v[26:29]
	v_mfma_f32_16x16x32_bf16 v[22:25], v[192:195], v[216:219], v[22:25]
	v_mfma_f32_16x16x32_bf16 v[18:21], v[192:195], v[224:227], v[18:21]
	v_mfma_f32_16x16x32_bf16 v[14:17], v[200:203], v[216:219], v[14:17]
	v_mfma_f32_16x16x32_bf16 v[10:13], v[200:203], v[224:227], v[10:13]
	v_mfma_f32_16x16x32_bf16 v[6:9], v[208:211], v[216:219], v[6:9]
	v_mfma_f32_16x16x32_bf16 v[2:5], v[208:211], v[224:227], v[2:5]
	s_add_u32 s6, s6, 0x100
	s_addc_u32 s7, s7, 0
	s_add_u32 s44, s44, 0x100
	s_addc_u32 s45, s45, 0
	s_add_u32 s50, s50, 0x100
	s_addc_u32 s51, s51, 0
	s_add_u32 s55, s55, 0x100
	s_addc_u32 s57, s57, 0
	s_cmp_ge_u32 s58, s43
	s_barrier
	s_cbranch_scc0 .LBB0_98
	s_add_i32 s4, s48, s14
	s_add_i32 s48, s4, -1
	s_lshl_b64 s[4:5], s[48:49], 7
	s_add_u32 s4, s22, s4
	s_addc_u32 s5, s23, s5
	s_add_u32 s4, s4, s40
	s_addc_u32 s5, s5, s39
	s_mov_b32 m0, s63
	ds_read_b128 v[148:151], v143
	ds_read_b128 v[152:155], v143 offset:1024
	ds_read_b128 v[156:159], v143 offset:2048
	ds_read_b128 v[160:163], v143 offset:3072
	ds_read_b128 v[164:167], v133
	ds_read_b128 v[184:187], v133 offset:1024
	ds_read_b128 v[188:191], v134
	ds_read_b128 v[192:195], v134 offset:1024
	ds_read_b128 v[196:199], v137
	ds_read_b128 v[200:203], v137 offset:1024
	ds_read_b128 v[204:207], v139
	ds_read_b128 v[208:211], v139 offset:1024
	s_nop 0
	v_lshl_add_u64 v[142:143], s[4:5], 0, v[0:1]
	global_load_lds_dwordx4 v[142:143], off
	v_lshl_add_u64 v[140:141], s[4:5], 0, v[140:141]
	s_mov_b32 m0, s59
	s_nop 0
	global_load_lds_dwordx4 v[140:141], off
	s_barrier
	s_waitcnt lgkmcnt(0)
	s_setprio 1
	s_waitcnt lgkmcnt(0)
	v_mfma_f32_16x16x32_bf16 v[126:129], v[164:167], v[148:151], v[126:129]
	v_mfma_f32_16x16x32_bf16 v[122:125], v[164:167], v[156:159], v[122:125]
	v_mfma_f32_16x16x32_bf16 v[118:121], v[188:191], v[148:151], v[118:121]
	v_mfma_f32_16x16x32_bf16 v[110:113], v[196:199], v[148:151], v[110:113]
	v_mfma_f32_16x16x32_bf16 v[106:109], v[196:199], v[156:159], v[106:109]
	v_mfma_f32_16x16x32_bf16 v[102:105], v[204:207], v[148:151], v[102:105]
	v_mfma_f32_16x16x32_bf16 v[98:101], v[204:207], v[156:159], v[98:101]
	v_mfma_f32_16x16x32_bf16 v[126:129], v[184:187], v[152:155], v[126:129]
	v_mfma_f32_16x16x32_bf16 v[122:125], v[184:187], v[160:163], v[122:125]
	v_mfma_f32_16x16x32_bf16 v[118:121], v[192:195], v[152:155], v[118:121]
	v_mfma_f32_16x16x32_bf16 v[114:117], v[188:191], v[156:159], v[114:117]
	v_mfma_f32_16x16x32_bf16 v[110:113], v[200:203], v[152:155], v[110:113]
	v_mfma_f32_16x16x32_bf16 v[106:109], v[200:203], v[160:163], v[106:109]
	v_mfma_f32_16x16x32_bf16 v[102:105], v[208:211], v[152:155], v[102:105]
	v_mfma_f32_16x16x32_bf16 v[98:101], v[208:211], v[160:163], v[98:101]
	v_mfma_f32_16x16x32_bf16 v[140:143], v[192:195], v[160:163], v[114:117]
	s_setprio 0
	s_barrier
	s_nop 0
	ds_read_b128 v[114:117], v144
	ds_read_b128 v[212:215], v144 offset:1024
	ds_read_b128 v[216:219], v144 offset:2048
	ds_read_b128 v[220:223], v144 offset:3072
	s_barrier
; #define LDA(dst, b, h) for (int m = 0; m < 4; ++m) for (int k = 0; k < 2; ++k) \
;     dst[m][k] = *reinterpret_cast<const bf16x8*>((char*)SA(b, h) + lds_byte(wr * 64 + m * 16 + fr, k * 32 + fq * 8))
; #define LDB(dst, b, h) for (int n = 0; n < 2; ++n) for (int k = 0; k < 2; ++k) \
;     dst[n][k] = *reinterpret_cast<const bf16x8*>((char*)SB(b, h) + lds_byte(wc * 32 + n * 16 + fr, k * 32 + fq * 8))
; #define MMA(ai, bj, At, Bt_) do { __builtin_amdgcn_s_setprio(1); \
;     for (int m = 0; m < 4; ++m) for (int n = 0; n < 2; ++n) for (int k = 0; k < 2; ++k) \
;       acc[ai][bj][m][n] = __builtin_amdgcn_mfma_f32_16x16x32_bf16(At[m][k], Bt_[n][k], acc[ai][bj][m][n], 0, 0, 0); \
;     __builtin_amdgcn_s_setprio(0); } while (0)
; #define WAIT_V(n) asm volatile("s_waitcnt vmcnt(" #n ")" ::: "memory")
; #define WAIT_L(n) asm volatile("s_waitcnt lgkmcnt(" #n ")" ::: "memory")
; #define BAR __builtin_amdgcn_s_barrier()
;     ...
;       LDB(B1, 0, 1); BAR; WAIT_L(0); MMA(0, 1, At, B1); BAR;
;       LDA(At, 0, 1); WAIT_V(4); BAR; WAIT_L(0); MMA(1, 0, At, B0); MMA(1, 1, At, B1); BAR; }
;     { LDB(B0, 1, 0); LDA(At, 1, 0); WAIT_V(2); BAR; WAIT_L(0); MMA(0, 0, At, B0); BAR;
	s_waitcnt lgkmcnt(0)
	s_setprio 1
	s_waitcnt lgkmcnt(0)
	v_mfma_f32_16x16x32_bf16 v[90:93], v[164:167], v[216:219], v[90:93]
	v_mfma_f32_16x16x32_bf16 v[86:89], v[188:191], v[114:117], v[86:89]
	v_mfma_f32_16x16x32_bf16 v[94:97], v[164:167], v[114:117], v[94:97]
	v_mfma_f32_16x16x32_bf16 v[90:93], v[184:187], v[220:223], v[90:93]
	v_mfma_f32_16x16x32_bf16 v[86:89], v[192:195], v[212:215], v[86:89]
	v_mfma_f32_16x16x32_bf16 v[82:85], v[188:191], v[216:219], v[82:85]
	v_mfma_f32_16x16x32_bf16 v[78:81], v[196:199], v[114:117], v[78:81]
	v_mfma_f32_16x16x32_bf16 v[74:77], v[196:199], v[216:219], v[74:77]
	v_mfma_f32_16x16x32_bf16 v[70:73], v[204:207], v[114:117], v[70:73]
	v_mfma_f32_16x16x32_bf16 v[66:69], v[204:207], v[216:219], v[66:69]
	v_mfma_f32_16x16x32_bf16 v[224:227], v[184:187], v[212:215], v[94:97]
	v_mfma_f32_16x16x32_bf16 v[164:167], v[192:195], v[220:223], v[82:85]
	v_mfma_f32_16x16x32_bf16 v[184:187], v[200:203], v[212:215], v[78:81]
	v_mfma_f32_16x16x32_bf16 v[188:191], v[200:203], v[220:223], v[74:77]
	v_mfma_f32_16x16x32_bf16 v[192:195], v[208:211], v[212:215], v[70:73]
	v_mfma_f32_16x16x32_bf16 v[196:199], v[208:211], v[220:223], v[66:69]
	s_setprio 0
	s_barrier
	s_nop 0
	ds_read_b128 v[66:69], v133 offset:16384
	ds_read_b128 v[70:73], v133 offset:17408
	ds_read_b128 v[74:77], v134 offset:16384
	ds_read_b128 v[78:81], v134 offset:17408
	ds_read_b128 v[82:85], v137 offset:16384
	ds_read_b128 v[94:97], v137 offset:17408
	ds_read_b128 v[200:203], v139 offset:16384
	ds_read_b128 v[204:207], v139 offset:17408
	s_waitcnt vmcnt(4)
	s_barrier
	s_waitcnt lgkmcnt(0)
	s_setprio 1
	s_waitcnt lgkmcnt(0)
	v_mfma_f32_16x16x32_bf16 v[62:65], v[66:69], v[148:151], v[62:65]
	v_mfma_f32_16x16x32_bf16 v[58:61], v[66:69], v[156:159], v[58:61]
	v_mfma_f32_16x16x32_bf16 v[54:57], v[74:77], v[148:151], v[54:57]
	v_mfma_f32_16x16x32_bf16 v[50:53], v[74:77], v[156:159], v[50:53]
	v_mfma_f32_16x16x32_bf16 v[46:49], v[82:85], v[148:151], v[46:49]
	v_mfma_f32_16x16x32_bf16 v[42:45], v[82:85], v[156:159], v[42:45]
	v_mfma_f32_16x16x32_bf16 v[38:41], v[200:203], v[148:151], v[38:41]
	v_mfma_f32_16x16x32_bf16 v[34:37], v[200:203], v[156:159], v[34:37]
	v_mfma_f32_16x16x32_bf16 v[62:65], v[70:73], v[152:155], v[62:65]
	v_mfma_f32_16x16x32_bf16 v[58:61], v[70:73], v[160:163], v[58:61]
	v_mfma_f32_16x16x32_bf16 v[54:57], v[78:81], v[152:155], v[54:57]
	v_mfma_f32_16x16x32_bf16 v[50:53], v[78:81], v[160:163], v[50:53]
	v_mfma_f32_16x16x32_bf16 v[46:49], v[94:97], v[152:155], v[46:49]
	v_mfma_f32_16x16x32_bf16 v[42:45], v[94:97], v[160:163], v[42:45]
	v_mfma_f32_16x16x32_bf16 v[38:41], v[204:207], v[152:155], v[38:41]
	v_mfma_f32_16x16x32_bf16 v[34:37], v[204:207], v[160:163], v[34:37]
	s_setprio 0
	s_setprio 1
	v_mfma_f32_16x16x32_bf16 v[30:33], v[66:69], v[114:117], v[30:33]
	v_mfma_f32_16x16x32_bf16 v[26:29], v[66:69], v[216:219], v[26:29]
	v_mfma_f32_16x16x32_bf16 v[22:25], v[74:77], v[114:117], v[22:25]
	v_mfma_f32_16x16x32_bf16 v[18:21], v[74:77], v[216:219], v[18:21]
	v_mfma_f32_16x16x32_bf16 v[14:17], v[82:85], v[114:117], v[14:17]
	v_mfma_f32_16x16x32_bf16 v[10:13], v[82:85], v[216:219], v[10:13]
	v_mfma_f32_16x16x32_bf16 v[6:9], v[200:203], v[114:117], v[6:9]
	v_mfma_f32_16x16x32_bf16 v[2:5], v[200:203], v[216:219], v[2:5]
	v_mfma_f32_16x16x32_bf16 v[148:151], v[70:73], v[212:215], v[30:33]
	v_mfma_f32_16x16x32_bf16 v[152:155], v[70:73], v[220:223], v[26:29]
	v_mfma_f32_16x16x32_bf16 v[156:159], v[78:81], v[212:215], v[22:25]
	v_mfma_f32_16x16x32_bf16 v[160:163], v[78:81], v[220:223], v[18:21]
	v_mfma_f32_16x16x32_bf16 v[208:211], v[94:97], v[212:215], v[14:17]
	v_mfma_f32_16x16x32_bf16 v[228:231], v[94:97], v[220:223], v[10:13]
	v_mfma_f32_16x16x32_bf16 v[212:215], v[204:207], v[212:215], v[6:9]
	v_mfma_f32_16x16x32_bf16 v[200:203], v[204:207], v[220:223], v[2:5]
	s_setprio 0
	s_barrier
	ds_read_b128 v[14:17], v145
	ds_read_b128 v[30:33], v145 offset:1024
	ds_read_b128 v[204:207], v145 offset:2048
	ds_read_b128 v[216:219], v145 offset:3072
	ds_read_b128 v[2:5], v133 offset:32768
	ds_read_b128 v[6:9], v133 offset:33792
	ds_read_b128 v[10:13], v134 offset:32768
	ds_read_b128 v[18:21], v134 offset:33792
	ds_read_b128 v[22:25], v137 offset:32768
	ds_read_b128 v[26:29], v137 offset:33792
	ds_read_b128 v[220:223], v139 offset:32768
	ds_read_b128 v[232:235], v139 offset:33792
	s_waitcnt vmcnt(2)
	s_barrier
; #define LDA(dst, b, h) for (int m = 0; m < 4; ++m) for (int k = 0; k < 2; ++k) \
;     dst[m][k] = *reinterpret_cast<const bf16x8*>((char*)SA(b, h) + lds_byte(wr * 64 + m * 16 + fr, k * 32 + fq * 8))
; #define LDB(dst, b, h) for (int n = 0; n < 2; ++n) for (int k = 0; k < 2; ++k) \
;     dst[n][k] = *reinterpret_cast<const bf16x8*>((char*)SB(b, h) + lds_byte(wc * 32 + n * 16 + fr, k * 32 + fq * 8))
; #define MMA(ai, bj, At, Bt_) do { __builtin_amdgcn_s_setprio(1); \
;     for (int m = 0; m < 4; ++m) for (int n = 0; n < 2; ++n) for (int k = 0; k < 2; ++k) \
;       acc[ai][bj][m][n] = __builtin_amdgcn_mfma_f32_16x16x32_bf16(At[m][k], Bt_[n][k], acc[ai][bj][m][n], 0, 0, 0); \
;     __builtin_amdgcn_s_setprio(0); } while (0)
; #define WAIT_V(n) asm volatile("s_waitcnt vmcnt(" #n ")" ::: "memory")
; #define WAIT_L(n) asm volatile("s_waitcnt lgkmcnt(" #n ")" ::: "memory")
; #define BAR __builtin_amdgcn_s_barrier()
;     ...
;     { LDB(B0, 1, 0); LDA(At, 1, 0); WAIT_V(2); BAR; WAIT_L(0); MMA(0, 0, At, B0); BAR;
;       LDB(B1, 1, 1); WAIT_V(0); BAR; WAIT_L(0); MMA(0, 1, At, B1); BAR;
;       LDA(At, 1, 1); BAR; WAIT_L(0); MMA(1, 0, At, B0); MMA(1, 1, At, B1); BAR; }
;     if (wr == 0) BAR;
	s_waitcnt lgkmcnt(0)
	s_setprio 1
	s_waitcnt lgkmcnt(0)
	v_mfma_f32_16x16x32_bf16 v[66:69], v[2:5], v[14:17], v[126:129]
	v_mfma_f32_16x16x32_bf16 v[114:117], v[6:9], v[30:33], v[66:69]
	v_mfma_f32_16x16x32_bf16 v[66:69], v[2:5], v[204:207], v[122:125]
	v_mfma_f32_16x16x32_bf16 v[126:129], v[6:9], v[216:219], v[66:69]
	v_mfma_f32_16x16x32_bf16 v[66:69], v[10:13], v[14:17], v[118:121]
	v_mfma_f32_16x16x32_bf16 v[82:85], v[18:21], v[30:33], v[66:69]
	v_mfma_f32_16x16x32_bf16 v[66:69], v[10:13], v[204:207], v[140:143]
	v_mfma_f32_16x16x32_bf16 v[94:97], v[18:21], v[216:219], v[66:69]
	v_mfma_f32_16x16x32_bf16 v[66:69], v[22:25], v[14:17], v[110:113]
	v_mfma_f32_16x16x32_bf16 v[74:77], v[26:29], v[30:33], v[66:69]
	v_mfma_f32_16x16x32_bf16 v[66:69], v[22:25], v[204:207], v[106:109]
	v_mfma_f32_16x16x32_bf16 v[78:81], v[26:29], v[216:219], v[66:69]
	v_mfma_f32_16x16x32_bf16 v[66:69], v[220:223], v[14:17], v[102:105]
	v_mfma_f32_16x16x32_bf16 v[70:73], v[220:223], v[204:207], v[98:101]
	v_mfma_f32_16x16x32_bf16 v[66:69], v[232:235], v[30:33], v[66:69]
	v_mfma_f32_16x16x32_bf16 v[70:73], v[232:235], v[216:219], v[70:73]
	s_setprio 0
	s_barrier
	ds_read_b128 v[140:143], v146
	ds_read_b128 v[236:239], v146 offset:1024
	ds_read_b128 v[240:243], v146 offset:2048
	ds_read_b128 v[144:147], v146 offset:3072
	s_waitcnt vmcnt(0)
	s_barrier
	s_waitcnt lgkmcnt(0)
	s_setprio 1
	s_waitcnt lgkmcnt(0)
	v_mfma_f32_16x16x32_bf16 v[98:101], v[2:5], v[140:143], v[224:227]
	v_mfma_f32_16x16x32_bf16 v[2:5], v[2:5], v[240:243], v[90:93]
	v_mfma_f32_16x16x32_bf16 v[118:121], v[6:9], v[144:147], v[2:5]
	v_mfma_f32_16x16x32_bf16 v[2:5], v[10:13], v[140:143], v[86:89]
	v_mfma_f32_16x16x32_bf16 v[102:105], v[18:21], v[236:239], v[2:5]
	v_mfma_f32_16x16x32_bf16 v[2:5], v[10:13], v[240:243], v[164:167]
	v_mfma_f32_16x16x32_bf16 v[122:125], v[18:21], v[144:147], v[2:5]
	v_mfma_f32_16x16x32_bf16 v[2:5], v[22:25], v[140:143], v[184:187]
	v_mfma_f32_16x16x32_bf16 v[90:93], v[26:29], v[236:239], v[2:5]
	v_mfma_f32_16x16x32_bf16 v[2:5], v[22:25], v[240:243], v[188:191]
	v_mfma_f32_16x16x32_bf16 v[110:113], v[26:29], v[144:147], v[2:5]
	v_mfma_f32_16x16x32_bf16 v[2:5], v[220:223], v[140:143], v[192:195]
	v_mfma_f32_16x16x32_bf16 v[86:89], v[232:235], v[236:239], v[2:5]
	v_mfma_f32_16x16x32_bf16 v[2:5], v[220:223], v[240:243], v[196:199]
	v_mfma_f32_16x16x32_bf16 v[98:101], v[6:9], v[236:239], v[98:101]
	v_mfma_f32_16x16x32_bf16 v[106:109], v[232:235], v[144:147], v[2:5]
	s_setprio 0
	s_barrier
	ds_read_b128 v[164:167], v133 offset:49152
	ds_read_b128 v[184:187], v133 offset:50176
	ds_read_b128 v[188:191], v134 offset:49152
	ds_read_b128 v[192:195], v134 offset:50176
	ds_read_b128 v[196:199], v137 offset:49152
	ds_read_b128 v[220:223], v137 offset:50176
	ds_read_b128 v[224:227], v139 offset:49152
	ds_read_b128 v[232:235], v139 offset:50176
	s_barrier
	s_waitcnt lgkmcnt(0)
	s_setprio 1
	s_waitcnt lgkmcnt(0)
	v_mfma_f32_16x16x32_bf16 v[6:9], v[164:167], v[204:207], v[58:61]
	v_mfma_f32_16x16x32_bf16 v[10:13], v[188:191], v[204:207], v[50:53]
	v_mfma_f32_16x16x32_bf16 v[2:5], v[164:167], v[14:17], v[62:65]
	v_mfma_f32_16x16x32_bf16 v[18:21], v[184:187], v[216:219], v[6:9]
	v_mfma_f32_16x16x32_bf16 v[6:9], v[188:191], v[14:17], v[54:57]
	v_mfma_f32_16x16x32_bf16 v[22:25], v[192:195], v[216:219], v[10:13]
	v_mfma_f32_16x16x32_bf16 v[10:13], v[196:199], v[14:17], v[46:49]
	v_mfma_f32_16x16x32_bf16 v[14:17], v[224:227], v[14:17], v[38:41]
	v_mfma_f32_16x16x32_bf16 v[2:5], v[184:187], v[30:33], v[2:5]
	v_mfma_f32_16x16x32_bf16 v[6:9], v[192:195], v[30:33], v[6:9]
	v_mfma_f32_16x16x32_bf16 v[10:13], v[220:223], v[30:33], v[10:13]
	v_mfma_f32_16x16x32_bf16 v[26:29], v[196:199], v[204:207], v[42:45]
	v_mfma_f32_16x16x32_bf16 v[14:17], v[232:235], v[30:33], v[14:17]
	v_mfma_f32_16x16x32_bf16 v[30:33], v[224:227], v[204:207], v[34:37]
	v_mfma_f32_16x16x32_bf16 v[26:29], v[220:223], v[216:219], v[26:29]
	v_mfma_f32_16x16x32_bf16 v[30:33], v[232:235], v[216:219], v[30:33]
	s_setprio 0
	s_setprio 1
	v_mfma_f32_16x16x32_bf16 v[38:41], v[164:167], v[240:243], v[152:155]
	v_mfma_f32_16x16x32_bf16 v[42:45], v[188:191], v[240:243], v[160:163]
	v_mfma_f32_16x16x32_bf16 v[46:49], v[196:199], v[240:243], v[228:231]
	v_mfma_f32_16x16x32_bf16 v[34:37], v[164:167], v[140:143], v[148:151]
	v_mfma_f32_16x16x32_bf16 v[50:53], v[184:187], v[144:147], v[38:41]
	v_mfma_f32_16x16x32_bf16 v[38:41], v[188:191], v[140:143], v[156:159]
	v_mfma_f32_16x16x32_bf16 v[54:57], v[192:195], v[144:147], v[42:45]
	v_mfma_f32_16x16x32_bf16 v[42:45], v[196:199], v[140:143], v[208:211]
	v_mfma_f32_16x16x32_bf16 v[58:61], v[220:223], v[144:147], v[46:49]
	v_mfma_f32_16x16x32_bf16 v[46:49], v[224:227], v[140:143], v[212:215]
	v_mfma_f32_16x16x32_bf16 v[62:65], v[224:227], v[240:243], v[200:203]
	v_mfma_f32_16x16x32_bf16 v[34:37], v[184:187], v[236:239], v[34:37]
	v_mfma_f32_16x16x32_bf16 v[38:41], v[192:195], v[236:239], v[38:41]
	v_mfma_f32_16x16x32_bf16 v[42:45], v[220:223], v[236:239], v[42:45]
	v_mfma_f32_16x16x32_bf16 v[46:49], v[232:235], v[236:239], v[46:49]
	v_mfma_f32_16x16x32_bf16 v[62:65], v[232:235], v[144:147], v[62:65]
	s_setprio 0
	v_readlane_b32 s4, v245, 33
	v_readlane_b32 s5, v245, 34
	s_and_b64 vcc, exec, s[4:5]
	s_barrier
	s_cbranch_vccz .LBB0_101
	s_barrier

; #define LDA(dst, b, h) for (int m = 0; m < 4; ++m) for (int k = 0; k < 2; ++k) \
;     dst[m][k] = *reinterpret_cast<const bf16x8*>((char*)SA(b, h) + lds_byte(wr * 64 + m * 16 + fr, k * 32 + fq * 8))
; #define LDB(dst, b, h) for (int n = 0; n < 2; ++n) for (int k = 0; k < 2; ++k) \
;     dst[n][k] = *reinterpret_cast<const bf16x8*>((char*)SB(b, h) + lds_byte(wc * 32 + n * 16 + fr, k * 32 + fq * 8))
; #define MMA(ai, bj, At, Bt_) do { __builtin_amdgcn_s_setprio(1); \
;     for (int m = 0; m < 4; ++m) for (int n = 0; n < 2; ++n) for (int k = 0; k < 2; ++k) \
;       acc[ai][bj][m][n] = __builtin_amdgcn_mfma_f32_16x16x32_bf16(At[m][k], Bt_[n][k], acc[ai][bj][m][n], 0, 0, 0); \
;     __builtin_amdgcn_s_setprio(0); } while (0)
; #define WAIT_L(n) asm volatile("s_waitcnt lgkmcnt(" #n ")" ::: "memory")
; #define BAR __builtin_amdgcn_s_barrier()
; #define SCHED __builtin_amdgcn_sched_barrier(0)
;     ...
;       LDB(B0, 0, 0); SCHED; LDA(At, 0, 0); STAGE(SA(1, 1), A, brow + HALF, t + 1);
;       WAIT_L(8); BAR; WAIT_L(0); MMA(0, 0, At, B0); BAR; SCHED;
;       LDB(B1, 0, 1); STAGE(SB(0, 0), Bt, bcol, t + 2);
;       BAR; WAIT_L(0); MMA(0, 1, At, B1); BAR;
;       LDA(At, 0, 1); STAGE(SA(0, 0), A, brow, t + 2);
;       BAR; WAIT_L(0); MMA(1, 0, At, B0); BAR; SCHED;
.LBB0_155:
	v_add_u32_e32 v143, s2, v142
	ds_read_b128 v[146:149], v143
	ds_read_b128 v[150:153], v143 offset:1024
	ds_read_b128 v[154:157], v143 offset:2048
	ds_read_b128 v[158:161], v143 offset:3072
	s_add_u32 s40, s30, s10
	s_addc_u32 s41, s31, s11
	s_add_u32 s42, s40, 0x80080
	s_addc_u32 s43, s41, 0
	s_add_i32 s39, s24, 0xc000
	ds_read_b128 v[162:165], v133
	ds_read_b128 v[184:187], v133 offset:1024
	ds_read_b128 v[188:191], v134
	ds_read_b128 v[192:195], v134 offset:1024
	ds_read_b128 v[196:199], v137
	ds_read_b128 v[200:203], v137 offset:1024
	ds_read_b128 v[204:207], v139
	ds_read_b128 v[208:211], v139 offset:1024
	s_mov_b32 m0, s39
	v_lshl_add_u64 v[144:145], s[42:43], 0, v[0:1]
	s_add_i32 s38, s24, 0xe000
	global_load_lds_dwordx4 v[144:145], off
	v_lshl_add_u64 v[144:145], s[42:43], 0, v[140:141]
	s_mov_b32 m0, s38
	s_nop 0
	global_load_lds_dwordx4 v[144:145], off
	s_waitcnt lgkmcnt(8)
	s_barrier
	s_waitcnt lgkmcnt(0)
	s_waitcnt lgkmcnt(0)
	v_mfma_f32_16x16x32_bf16 v[126:129], v[162:165], v[146:149], v[126:129]
	v_mfma_f32_16x16x32_bf16 v[122:125], v[162:165], v[154:157], v[122:125]
	v_mfma_f32_16x16x32_bf16 v[118:121], v[188:191], v[146:149], v[118:121]
	v_mfma_f32_16x16x32_bf16 v[114:117], v[188:191], v[154:157], v[114:117]
	v_mfma_f32_16x16x32_bf16 v[110:113], v[196:199], v[146:149], v[110:113]
	v_mfma_f32_16x16x32_bf16 v[106:109], v[196:199], v[154:157], v[106:109]
	v_mfma_f32_16x16x32_bf16 v[102:105], v[204:207], v[146:149], v[102:105]
	v_mfma_f32_16x16x32_bf16 v[98:101], v[204:207], v[154:157], v[98:101]
	v_mfma_f32_16x16x32_bf16 v[126:129], v[184:187], v[150:153], v[126:129]
	v_mfma_f32_16x16x32_bf16 v[122:125], v[184:187], v[158:161], v[122:125]
	v_mfma_f32_16x16x32_bf16 v[118:121], v[192:195], v[150:153], v[118:121]
	v_mfma_f32_16x16x32_bf16 v[114:117], v[192:195], v[158:161], v[114:117]
	v_mfma_f32_16x16x32_bf16 v[110:113], v[200:203], v[150:153], v[110:113]
	v_mfma_f32_16x16x32_bf16 v[106:109], v[200:203], v[158:161], v[106:109]
	v_mfma_f32_16x16x32_bf16 v[102:105], v[208:211], v[150:153], v[102:105]
	v_mfma_f32_16x16x32_bf16 v[98:101], v[208:211], v[158:161], v[98:101]
	s_barrier
	s_add_u32 s42, s34, s10
	s_addc_u32 s43, s35, s11
	s_add_u32 s44, s42, 0x100
	v_add_u32_e32 v144, s76, v142
	s_addc_u32 s45, s43, 0
	s_mov_b32 m0, s25
	ds_read_b128 v[212:215], v144
	ds_read_b128 v[216:219], v144 offset:1024
	ds_read_b128 v[220:223], v144 offset:2048
	ds_read_b128 v[224:227], v144 offset:3072
	s_nop 0
	v_lshl_add_u64 v[166:167], s[44:45], 0, v[0:1]
	global_load_lds_dwordx4 v[166:167], off
	v_lshl_add_u64 v[166:167], s[44:45], 0, v[140:141]
	s_mov_b32 m0, s26
	s_nop 0
	global_load_lds_dwordx4 v[166:167], off
	s_barrier
	s_waitcnt lgkmcnt(0)
	s_waitcnt lgkmcnt(0)
	v_mfma_f32_16x16x32_bf16 v[94:97], v[162:165], v[212:215], v[94:97]
	v_mfma_f32_16x16x32_bf16 v[90:93], v[162:165], v[220:223], v[90:93]
	v_mfma_f32_16x16x32_bf16 v[86:89], v[188:191], v[212:215], v[86:89]
	v_mfma_f32_16x16x32_bf16 v[82:85], v[188:191], v[220:223], v[82:85]
	v_mfma_f32_16x16x32_bf16 v[78:81], v[196:199], v[212:215], v[78:81]
	v_mfma_f32_16x16x32_bf16 v[74:77], v[196:199], v[220:223], v[74:77]
	v_mfma_f32_16x16x32_bf16 v[70:73], v[204:207], v[212:215], v[70:73]
	v_mfma_f32_16x16x32_bf16 v[66:69], v[204:207], v[220:223], v[66:69]
	v_mfma_f32_16x16x32_bf16 v[94:97], v[184:187], v[216:219], v[94:97]
	v_mfma_f32_16x16x32_bf16 v[90:93], v[184:187], v[224:227], v[90:93]
	v_mfma_f32_16x16x32_bf16 v[86:89], v[192:195], v[216:219], v[86:89]
	v_mfma_f32_16x16x32_bf16 v[82:85], v[192:195], v[224:227], v[82:85]
	v_mfma_f32_16x16x32_bf16 v[78:81], v[200:203], v[216:219], v[78:81]
	v_mfma_f32_16x16x32_bf16 v[74:77], v[200:203], v[224:227], v[74:77]
	v_mfma_f32_16x16x32_bf16 v[70:73], v[208:211], v[216:219], v[70:73]
	v_mfma_f32_16x16x32_bf16 v[66:69], v[208:211], v[224:227], v[66:69]
	s_add_u32 s44, s40, 0x100
	s_addc_u32 s45, s41, 0
	s_mov_b32 m0, s24
	s_barrier
	ds_read_b128 v[162:165], v133 offset:16384
	ds_read_b128 v[184:187], v133 offset:17408
	ds_read_b128 v[188:191], v134 offset:16384
	ds_read_b128 v[192:195], v134 offset:17408
	ds_read_b128 v[196:199], v137 offset:16384
	ds_read_b128 v[200:203], v137 offset:17408
	ds_read_b128 v[204:207], v139 offset:16384
	ds_read_b128 v[208:211], v139 offset:17408
	s_nop 0
	v_lshl_add_u64 v[166:167], s[44:45], 0, v[0:1]
	global_load_lds_dwordx4 v[166:167], off
	v_lshl_add_u64 v[166:167], s[44:45], 0, v[140:141]
	s_mov_b32 m0, s9
	s_nop 0
	global_load_lds_dwordx4 v[166:167], off
	s_barrier
	s_waitcnt lgkmcnt(0)
	s_waitcnt lgkmcnt(0)
	v_mfma_f32_16x16x32_bf16 v[62:65], v[162:165], v[146:149], v[62:65]
	v_mfma_f32_16x16x32_bf16 v[58:61], v[162:165], v[154:157], v[58:61]
	v_mfma_f32_16x16x32_bf16 v[54:57], v[188:191], v[146:149], v[54:57]
	v_mfma_f32_16x16x32_bf16 v[50:53], v[188:191], v[154:157], v[50:53]
	v_mfma_f32_16x16x32_bf16 v[46:49], v[196:199], v[146:149], v[46:49]
	v_mfma_f32_16x16x32_bf16 v[42:45], v[196:199], v[154:157], v[42:45]
	v_mfma_f32_16x16x32_bf16 v[38:41], v[204:207], v[146:149], v[38:41]
	v_mfma_f32_16x16x32_bf16 v[34:37], v[204:207], v[154:157], v[34:37]
	v_mfma_f32_16x16x32_bf16 v[62:65], v[184:187], v[150:153], v[62:65]
	v_mfma_f32_16x16x32_bf16 v[58:61], v[184:187], v[158:161], v[58:61]
	v_mfma_f32_16x16x32_bf16 v[54:57], v[192:195], v[150:153], v[54:57]
	v_mfma_f32_16x16x32_bf16 v[50:53], v[192:195], v[158:161], v[50:53]
	v_mfma_f32_16x16x32_bf16 v[46:49], v[200:203], v[150:153], v[46:49]
	v_mfma_f32_16x16x32_bf16 v[42:45], v[200:203], v[158:161], v[42:45]
	v_mfma_f32_16x16x32_bf16 v[38:41], v[208:211], v[150:153], v[38:41]
	v_mfma_f32_16x16x32_bf16 v[34:37], v[208:211], v[158:161], v[34:37]
	s_barrier
; #define LDA(dst, b, h) for (int m = 0; m < 4; ++m) for (int k = 0; k < 2; ++k) \
;     dst[m][k] = *reinterpret_cast<const bf16x8*>((char*)SA(b, h) + lds_byte(wr * 64 + m * 16 + fr, k * 32 + fq * 8))
; #define LDB(dst, b, h) for (int n = 0; n < 2; ++n) for (int k = 0; k < 2; ++k) \
;     dst[n][k] = *reinterpret_cast<const bf16x8*>((char*)SB(b, h) + lds_byte(wc * 32 + n * 16 + fr, k * 32 + fq * 8))
; #define MMA(ai, bj, At, Bt_) do { __builtin_amdgcn_s_setprio(1); \
;     for (int m = 0; m < 4; ++m) for (int n = 0; n < 2; ++n) for (int k = 0; k < 2; ++k) \
;       acc[ai][bj][m][n] = __builtin_amdgcn_mfma_f32_16x16x32_bf16(At[m][k], Bt_[n][k], acc[ai][bj][m][n], 0, 0, 0); \
;     __builtin_amdgcn_s_setprio(0); } while (0)
; #define WAIT_V(n) asm volatile("s_waitcnt vmcnt(" #n ")" ::: "memory")
; #define WAIT_L(n) asm volatile("s_waitcnt lgkmcnt(" #n ")" ::: "memory")
; #define BAR __builtin_amdgcn_s_barrier()
; #define SCHED __builtin_amdgcn_sched_barrier(0)
;     ...
;       STAGE(SB(0, 1), Bt, bcol + HALF, t + 2);
;       WAIT_V(6); BAR; MMA(1, 1, At, B1); BAR;
;       LDB(B0, 1, 0); SCHED; LDA(At, 1, 0); STAGE(SA(0, 1), A, brow + HALF, t + 2);
;       WAIT_L(8); BAR; WAIT_L(0); MMA(0, 0, At, B0); BAR; SCHED;
;       LDB(B1, 1, 1); STAGE(SB(1, 0), Bt, bcol, t + 3);
;       BAR; WAIT_L(0); MMA(0, 1, At, B1); BAR;
;       LDA(At, 1, 1); STAGE(SA(1, 0), A, brow, t + 3);
	s_add_u32 s44, s42, 0x80100
	s_addc_u32 s45, s43, 0
	s_mov_b32 m0, s27
	s_nop 0
	v_lshl_add_u64 v[146:147], s[44:45], 0, v[0:1]
	global_load_lds_dwordx4 v[146:147], off
	v_lshl_add_u64 v[146:147], s[44:45], 0, v[140:141]
	s_mov_b32 m0, s28
	s_nop 0
	global_load_lds_dwordx4 v[146:147], off
	s_waitcnt vmcnt(6)
	s_barrier
	v_mfma_f32_16x16x32_bf16 v[30:33], v[162:165], v[212:215], v[30:33]
	v_mfma_f32_16x16x32_bf16 v[26:29], v[162:165], v[220:223], v[26:29]
	v_mfma_f32_16x16x32_bf16 v[22:25], v[188:191], v[212:215], v[22:25]
	v_mfma_f32_16x16x32_bf16 v[18:21], v[188:191], v[220:223], v[18:21]
	v_mfma_f32_16x16x32_bf16 v[14:17], v[196:199], v[212:215], v[14:17]
	v_mfma_f32_16x16x32_bf16 v[10:13], v[196:199], v[220:223], v[10:13]
	v_mfma_f32_16x16x32_bf16 v[6:9], v[204:207], v[212:215], v[6:9]
	v_mfma_f32_16x16x32_bf16 v[2:5], v[204:207], v[220:223], v[2:5]
	v_mfma_f32_16x16x32_bf16 v[30:33], v[184:187], v[216:219], v[30:33]
	v_mfma_f32_16x16x32_bf16 v[26:29], v[184:187], v[224:227], v[26:29]
	v_mfma_f32_16x16x32_bf16 v[22:25], v[192:195], v[216:219], v[22:25]
	v_mfma_f32_16x16x32_bf16 v[18:21], v[192:195], v[224:227], v[18:21]
	v_mfma_f32_16x16x32_bf16 v[14:17], v[200:203], v[216:219], v[14:17]
	v_mfma_f32_16x16x32_bf16 v[10:13], v[200:203], v[224:227], v[10:13]
	v_mfma_f32_16x16x32_bf16 v[6:9], v[208:211], v[216:219], v[6:9]
	v_mfma_f32_16x16x32_bf16 v[2:5], v[208:211], v[224:227], v[2:5]
	v_add_u32_e32 v145, s77, v142
	s_barrier
	ds_read_b128 v[148:151], v145
	ds_read_b128 v[152:155], v145 offset:1024
	ds_read_b128 v[156:159], v145 offset:2048
	ds_read_b128 v[160:163], v145 offset:3072
	s_add_u32 s44, s40, 0x80100
	s_addc_u32 s45, s41, 0
	s_mov_b32 m0, s7
	ds_read_b128 v[164:167], v133 offset:32768
	ds_read_b128 v[184:187], v133 offset:33792
	ds_read_b128 v[188:191], v134 offset:32768
	ds_read_b128 v[192:195], v134 offset:33792
	ds_read_b128 v[196:199], v137 offset:32768
	ds_read_b128 v[200:203], v137 offset:33792
	ds_read_b128 v[204:207], v139 offset:32768
	ds_read_b128 v[208:211], v139 offset:33792
	s_nop 0
	v_lshl_add_u64 v[146:147], s[44:45], 0, v[0:1]
	global_load_lds_dwordx4 v[146:147], off
	v_lshl_add_u64 v[146:147], s[44:45], 0, v[140:141]
	s_mov_b32 m0, s29
	s_nop 0
	global_load_lds_dwordx4 v[146:147], off
	s_waitcnt lgkmcnt(8)
	s_barrier
	s_waitcnt lgkmcnt(0)
	s_waitcnt lgkmcnt(0)
	v_mfma_f32_16x16x32_bf16 v[126:129], v[164:167], v[148:151], v[126:129]
	v_mfma_f32_16x16x32_bf16 v[122:125], v[164:167], v[156:159], v[122:125]
	v_mfma_f32_16x16x32_bf16 v[118:121], v[188:191], v[148:151], v[118:121]
	v_mfma_f32_16x16x32_bf16 v[114:117], v[188:191], v[156:159], v[114:117]
	v_mfma_f32_16x16x32_bf16 v[110:113], v[196:199], v[148:151], v[110:113]
	v_mfma_f32_16x16x32_bf16 v[106:109], v[196:199], v[156:159], v[106:109]
	v_mfma_f32_16x16x32_bf16 v[102:105], v[204:207], v[148:151], v[102:105]
	v_mfma_f32_16x16x32_bf16 v[98:101], v[204:207], v[156:159], v[98:101]
	v_mfma_f32_16x16x32_bf16 v[126:129], v[184:187], v[152:155], v[126:129]
	v_mfma_f32_16x16x32_bf16 v[122:125], v[184:187], v[160:163], v[122:125]
	v_mfma_f32_16x16x32_bf16 v[118:121], v[192:195], v[152:155], v[118:121]
	v_mfma_f32_16x16x32_bf16 v[114:117], v[192:195], v[160:163], v[114:117]
	v_mfma_f32_16x16x32_bf16 v[110:113], v[200:203], v[152:155], v[110:113]
	v_mfma_f32_16x16x32_bf16 v[106:109], v[200:203], v[160:163], v[106:109]
	v_mfma_f32_16x16x32_bf16 v[102:105], v[208:211], v[152:155], v[102:105]
	v_mfma_f32_16x16x32_bf16 v[98:101], v[208:211], v[160:163], v[98:101]
	s_barrier
	s_add_u32 s44, s42, 0x180
	v_add_u32_e32 v146, s78, v142
	s_addc_u32 s45, s43, 0
	s_mov_b32 m0, s12
	ds_read_b128 v[212:215], v146
	ds_read_b128 v[216:219], v146 offset:1024
	ds_read_b128 v[220:223], v146 offset:2048
	ds_read_b128 v[224:227], v146 offset:3072
	s_nop 0
	v_lshl_add_u64 v[228:229], s[44:45], 0, v[0:1]
	global_load_lds_dwordx4 v[228:229], off
	v_lshl_add_u64 v[228:229], s[44:45], 0, v[140:141]
	s_mov_b32 m0, s13
	s_nop 0
	global_load_lds_dwordx4 v[228:229], off
	s_barrier
	s_waitcnt lgkmcnt(0)
	s_waitcnt lgkmcnt(0)
	v_mfma_f32_16x16x32_bf16 v[94:97], v[164:167], v[212:215], v[94:97]
	v_mfma_f32_16x16x32_bf16 v[90:93], v[164:167], v[220:223], v[90:93]
	v_mfma_f32_16x16x32_bf16 v[86:89], v[188:191], v[212:215], v[86:89]
	v_mfma_f32_16x16x32_bf16 v[82:85], v[188:191], v[220:223], v[82:85]
	v_mfma_f32_16x16x32_bf16 v[78:81], v[196:199], v[212:215], v[78:81]
	v_mfma_f32_16x16x32_bf16 v[74:77], v[196:199], v[220:223], v[74:77]
	v_mfma_f32_16x16x32_bf16 v[70:73], v[204:207], v[212:215], v[70:73]
	v_mfma_f32_16x16x32_bf16 v[66:69], v[204:207], v[220:223], v[66:69]
	v_mfma_f32_16x16x32_bf16 v[94:97], v[184:187], v[216:219], v[94:97]
	v_mfma_f32_16x16x32_bf16 v[90:93], v[184:187], v[224:227], v[90:93]
	v_mfma_f32_16x16x32_bf16 v[86:89], v[192:195], v[216:219], v[86:89]
	v_mfma_f32_16x16x32_bf16 v[82:85], v[192:195], v[224:227], v[82:85]
	v_mfma_f32_16x16x32_bf16 v[78:81], v[200:203], v[216:219], v[78:81]
	v_mfma_f32_16x16x32_bf16 v[74:77], v[200:203], v[224:227], v[74:77]
	v_mfma_f32_16x16x32_bf16 v[70:73], v[208:211], v[216:219], v[70:73]
	v_mfma_f32_16x16x32_bf16 v[66:69], v[208:211], v[224:227], v[66:69]
	s_add_u32 s40, s40, 0x180
	s_addc_u32 s41, s41, 0
	s_mov_b32 m0, s14
	s_barrier
	ds_read_b128 v[164:167], v133 offset:49152
	ds_read_b128 v[184:187], v133 offset:50176
	ds_read_b128 v[188:191], v134 offset:49152
	ds_read_b128 v[192:195], v134 offset:50176
	ds_read_b128 v[196:199], v137 offset:49152
	ds_read_b128 v[200:203], v137 offset:50176
	ds_read_b128 v[204:207], v139 offset:49152
	ds_read_b128 v[208:211], v139 offset:50176
	s_nop 0
	v_lshl_add_u64 v[228:229], s[40:41], 0, v[0:1]
	global_load_lds_dwordx4 v[228:229], off
	v_lshl_add_u64 v[228:229], s[40:41], 0, v[140:141]
	s_mov_b32 m0, s15
	s_nop 0
	global_load_lds_dwordx4 v[228:229], off
	s_barrier
; #define LDA(dst, b, h) for (int m = 0; m < 4; ++m) for (int k = 0; k < 2; ++k) \
;     dst[m][k] = *reinterpret_cast<const bf16x8*>((char*)SA(b, h) + lds_byte(wr * 64 + m * 16 + fr, k * 32 + fq * 8))
; #define LDB(dst, b, h) for (int n = 0; n < 2; ++n) for (int k = 0; k < 2; ++k) \
;     dst[n][k] = *reinterpret_cast<const bf16x8*>((char*)SB(b, h) + lds_byte(wc * 32 + n * 16 + fr, k * 32 + fq * 8))
; #define MMA(ai, bj, At, Bt_) do { __builtin_amdgcn_s_setprio(1); \
;     for (int m = 0; m < 4; ++m) for (int n = 0; n < 2; ++n) for (int k = 0; k < 2; ++k) \
;       acc[ai][bj][m][n] = __builtin_amdgcn_mfma_f32_16x16x32_bf16(At[m][k], Bt_[n][k], acc[ai][bj][m][n], 0, 0, 0); \
;     __builtin_amdgcn_s_setprio(0); } while (0)
; #define WAIT_V(n) asm volatile("s_waitcnt vmcnt(" #n ")" ::: "memory")
; #define WAIT_L(n) asm volatile("s_waitcnt lgkmcnt(" #n ")" ::: "memory")
; #define BAR __builtin_amdgcn_s_barrier()
; #define SCHED __builtin_amdgcn_sched_barrier(0)
;     ...
;       BAR; WAIT_L(0); MMA(1, 0, At, B0); BAR; SCHED;
;       STAGE(SB(1, 1), Bt, bcol + HALF, t + 3);
;       WAIT_V(6); BAR; MMA(1, 1, At, B1); BAR;
;     }
;     { LDB(B0, 0, 0); LDA(At, 0, 0); STAGE(SA(1, 1), A, brow + HALF, nt - 1);
;       BAR; WAIT_L(0); MMA(0, 0, At, B0); BAR;
;       LDB(B1, 0, 1); BAR; WAIT_L(0); MMA(0, 1, At, B1); BAR;
	s_waitcnt lgkmcnt(0)
	s_waitcnt lgkmcnt(0)
	v_mfma_f32_16x16x32_bf16 v[62:65], v[164:167], v[148:151], v[62:65]
	v_mfma_f32_16x16x32_bf16 v[58:61], v[164:167], v[156:159], v[58:61]
	v_mfma_f32_16x16x32_bf16 v[54:57], v[188:191], v[148:151], v[54:57]
	v_mfma_f32_16x16x32_bf16 v[50:53], v[188:191], v[156:159], v[50:53]
	v_mfma_f32_16x16x32_bf16 v[46:49], v[196:199], v[148:151], v[46:49]
	v_mfma_f32_16x16x32_bf16 v[42:45], v[196:199], v[156:159], v[42:45]
	v_mfma_f32_16x16x32_bf16 v[38:41], v[204:207], v[148:151], v[38:41]
	v_mfma_f32_16x16x32_bf16 v[34:37], v[204:207], v[156:159], v[34:37]
	v_mfma_f32_16x16x32_bf16 v[62:65], v[184:187], v[152:155], v[62:65]
	v_mfma_f32_16x16x32_bf16 v[58:61], v[184:187], v[160:163], v[58:61]
	v_mfma_f32_16x16x32_bf16 v[54:57], v[192:195], v[152:155], v[54:57]
	v_mfma_f32_16x16x32_bf16 v[50:53], v[192:195], v[160:163], v[50:53]
	v_mfma_f32_16x16x32_bf16 v[46:49], v[200:203], v[152:155], v[46:49]
	v_mfma_f32_16x16x32_bf16 v[42:45], v[200:203], v[160:163], v[42:45]
	v_mfma_f32_16x16x32_bf16 v[38:41], v[208:211], v[152:155], v[38:41]
	v_mfma_f32_16x16x32_bf16 v[34:37], v[208:211], v[160:163], v[34:37]
	s_barrier
	s_add_u32 s40, s42, 0x80180
	s_addc_u32 s41, s43, 0
	s_mov_b32 m0, s16
	s_nop 0
	v_lshl_add_u64 v[148:149], s[40:41], 0, v[0:1]
	global_load_lds_dwordx4 v[148:149], off
	v_lshl_add_u64 v[148:149], s[40:41], 0, v[140:141]
	s_mov_b32 m0, s17
	s_nop 0
	global_load_lds_dwordx4 v[148:149], off
	s_waitcnt vmcnt(6)
	s_barrier
	v_mfma_f32_16x16x32_bf16 v[30:33], v[164:167], v[212:215], v[30:33]
	v_mfma_f32_16x16x32_bf16 v[26:29], v[164:167], v[220:223], v[26:29]
	v_mfma_f32_16x16x32_bf16 v[22:25], v[188:191], v[212:215], v[22:25]
	v_mfma_f32_16x16x32_bf16 v[18:21], v[188:191], v[220:223], v[18:21]
	v_mfma_f32_16x16x32_bf16 v[14:17], v[196:199], v[212:215], v[14:17]
	v_mfma_f32_16x16x32_bf16 v[10:13], v[196:199], v[220:223], v[10:13]
	v_mfma_f32_16x16x32_bf16 v[6:9], v[204:207], v[212:215], v[6:9]
	v_mfma_f32_16x16x32_bf16 v[2:5], v[204:207], v[220:223], v[2:5]
	v_mfma_f32_16x16x32_bf16 v[30:33], v[184:187], v[216:219], v[30:33]
	v_mfma_f32_16x16x32_bf16 v[26:29], v[184:187], v[224:227], v[26:29]
	v_mfma_f32_16x16x32_bf16 v[22:25], v[192:195], v[216:219], v[22:25]
	v_mfma_f32_16x16x32_bf16 v[18:21], v[192:195], v[224:227], v[18:21]
	v_mfma_f32_16x16x32_bf16 v[14:17], v[200:203], v[216:219], v[14:17]
	v_mfma_f32_16x16x32_bf16 v[10:13], v[200:203], v[224:227], v[10:13]
	v_mfma_f32_16x16x32_bf16 v[6:9], v[208:211], v[216:219], v[6:9]
	v_mfma_f32_16x16x32_bf16 v[2:5], v[208:211], v[224:227], v[2:5]
	s_add_i32 s37, s37, 2
	s_add_u32 s10, s10, 0x100
	s_addc_u32 s11, s11, 0
	s_cmp_gt_u32 s37, 27
	s_barrier
	s_cbranch_scc0 .LBB0_155
	s_add_u32 s4, s4, 0xf80
	s_addc_u32 s5, s5, 0
	s_mov_b32 m0, s39
	ds_read_b128 v[148:151], v143
	ds_read_b128 v[152:155], v143 offset:1024
	ds_read_b128 v[156:159], v143 offset:2048
	ds_read_b128 v[160:163], v143 offset:3072
	ds_read_b128 v[164:167], v133
	ds_read_b128 v[184:187], v133 offset:1024
	ds_read_b128 v[188:191], v134
	ds_read_b128 v[192:195], v134 offset:1024
	ds_read_b128 v[196:199], v137
	ds_read_b128 v[200:203], v137 offset:1024
	ds_read_b128 v[204:207], v139
	ds_read_b128 v[208:211], v139 offset:1024
	s_nop 0
	v_lshl_add_u64 v[142:143], s[4:5], 0, v[0:1]
	global_load_lds_dwordx4 v[142:143], off
	v_lshl_add_u64 v[140:141], s[4:5], 0, v[140:141]
	s_mov_b32 m0, s38
	s_nop 0
	global_load_lds_dwordx4 v[140:141], off
	s_barrier
	s_waitcnt lgkmcnt(0)
	s_setprio 1
	s_waitcnt lgkmcnt(0)
	v_mfma_f32_16x16x32_bf16 v[126:129], v[164:167], v[148:151], v[126:129]
	v_mfma_f32_16x16x32_bf16 v[118:121], v[188:191], v[148:151], v[118:121]
	v_mfma_f32_16x16x32_bf16 v[110:113], v[196:199], v[148:151], v[110:113]
	v_mfma_f32_16x16x32_bf16 v[102:105], v[204:207], v[148:151], v[102:105]
	v_mfma_f32_16x16x32_bf16 v[126:129], v[184:187], v[152:155], v[126:129]
	v_mfma_f32_16x16x32_bf16 v[122:125], v[164:167], v[156:159], v[122:125]
	v_mfma_f32_16x16x32_bf16 v[118:121], v[192:195], v[152:155], v[118:121]
	v_mfma_f32_16x16x32_bf16 v[114:117], v[188:191], v[156:159], v[114:117]
	v_mfma_f32_16x16x32_bf16 v[110:113], v[200:203], v[152:155], v[110:113]
	v_mfma_f32_16x16x32_bf16 v[106:109], v[196:199], v[156:159], v[106:109]
	v_mfma_f32_16x16x32_bf16 v[102:105], v[208:211], v[152:155], v[102:105]
	v_mfma_f32_16x16x32_bf16 v[98:101], v[204:207], v[156:159], v[98:101]
	v_mfma_f32_16x16x32_bf16 v[140:143], v[184:187], v[160:163], v[122:125]
	v_mfma_f32_16x16x32_bf16 v[212:215], v[192:195], v[160:163], v[114:117]
	v_mfma_f32_16x16x32_bf16 v[216:219], v[200:203], v[160:163], v[106:109]
	v_mfma_f32_16x16x32_bf16 v[220:223], v[208:211], v[160:163], v[98:101]
	s_setprio 0
	s_barrier
	s_nop 1
	ds_read_b128 v[98:101], v144
	ds_read_b128 v[106:109], v144 offset:1024
	ds_read_b128 v[114:117], v144 offset:2048
	ds_read_b128 v[122:125], v144 offset:3072
	s_barrier
	s_waitcnt lgkmcnt(0)
	s_setprio 1
	s_waitcnt lgkmcnt(0)
	v_mfma_f32_16x16x32_bf16 v[94:97], v[164:167], v[98:101], v[94:97]
	v_mfma_f32_16x16x32_bf16 v[86:89], v[188:191], v[98:101], v[86:89]
	v_mfma_f32_16x16x32_bf16 v[78:81], v[196:199], v[98:101], v[78:81]
	v_mfma_f32_16x16x32_bf16 v[70:73], v[204:207], v[98:101], v[70:73]
	v_mfma_f32_16x16x32_bf16 v[94:97], v[184:187], v[106:109], v[94:97]
	v_mfma_f32_16x16x32_bf16 v[90:93], v[164:167], v[114:117], v[90:93]
	v_mfma_f32_16x16x32_bf16 v[86:89], v[192:195], v[106:109], v[86:89]
	v_mfma_f32_16x16x32_bf16 v[82:85], v[188:191], v[114:117], v[82:85]
	v_mfma_f32_16x16x32_bf16 v[78:81], v[200:203], v[106:109], v[78:81]
	v_mfma_f32_16x16x32_bf16 v[74:77], v[196:199], v[114:117], v[74:77]
	v_mfma_f32_16x16x32_bf16 v[70:73], v[208:211], v[106:109], v[70:73]
	v_mfma_f32_16x16x32_bf16 v[66:69], v[204:207], v[114:117], v[66:69]
	v_mfma_f32_16x16x32_bf16 v[164:167], v[184:187], v[122:125], v[90:93]
	v_mfma_f32_16x16x32_bf16 v[184:187], v[192:195], v[122:125], v[82:85]
	v_mfma_f32_16x16x32_bf16 v[188:191], v[200:203], v[122:125], v[74:77]
	v_mfma_f32_16x16x32_bf16 v[192:195], v[208:211], v[122:125], v[66:69]
	s_setprio 0
	s_barrier
; #define LDA(dst, b, h) for (int m = 0; m < 4; ++m) for (int k = 0; k < 2; ++k) \
;     dst[m][k] = *reinterpret_cast<const bf16x8*>((char*)SA(b, h) + lds_byte(wr * 64 + m * 16 + fr, k * 32 + fq * 8))
; #define LDB(dst, b, h) for (int n = 0; n < 2; ++n) for (int k = 0; k < 2; ++k) \
;     dst[n][k] = *reinterpret_cast<const bf16x8*>((char*)SB(b, h) + lds_byte(wc * 32 + n * 16 + fr, k * 32 + fq * 8))
; #define MMA(ai, bj, At, Bt_) do { __builtin_amdgcn_s_setprio(1); \
;     for (int m = 0; m < 4; ++m) for (int n = 0; n < 2; ++n) for (int k = 0; k < 2; ++k) \
;       acc[ai][bj][m][n] = __builtin_amdgcn_mfma_f32_16x16x32_bf16(At[m][k], Bt_[n][k], acc[ai][bj][m][n], 0, 0, 0); \
;     __builtin_amdgcn_s_setprio(0); } while (0)
; #define WAIT_V(n) asm volatile("s_waitcnt vmcnt(" #n ")" ::: "memory")
; #define WAIT_L(n) asm volatile("s_waitcnt lgkmcnt(" #n ")" ::: "memory")
; #define BAR __builtin_amdgcn_s_barrier()
;     ...
;       LDA(At, 0, 1); WAIT_V(4); BAR; WAIT_L(0); MMA(1, 0, At, B0); MMA(1, 1, At, B1); BAR; }
;     { LDB(B0, 1, 0); LDA(At, 1, 0); WAIT_V(2); BAR; WAIT_L(0); MMA(0, 0, At, B0); BAR;
	s_nop 1
	ds_read_b128 v[66:69], v133 offset:16384
	ds_read_b128 v[74:77], v133 offset:17408
	ds_read_b128 v[82:85], v134 offset:16384
	ds_read_b128 v[90:93], v134 offset:17408
	ds_read_b128 v[196:199], v137 offset:16384
	ds_read_b128 v[200:203], v137 offset:17408
	ds_read_b128 v[204:207], v139 offset:16384
	ds_read_b128 v[208:211], v139 offset:17408
	s_waitcnt vmcnt(4)
	s_barrier
	s_waitcnt lgkmcnt(0)
	s_setprio 1
	s_waitcnt lgkmcnt(0)
	v_mfma_f32_16x16x32_bf16 v[62:65], v[66:69], v[148:151], v[62:65]
	v_mfma_f32_16x16x32_bf16 v[54:57], v[82:85], v[148:151], v[54:57]
	v_mfma_f32_16x16x32_bf16 v[46:49], v[196:199], v[148:151], v[46:49]
	v_mfma_f32_16x16x32_bf16 v[38:41], v[204:207], v[148:151], v[38:41]
	v_mfma_f32_16x16x32_bf16 v[62:65], v[74:77], v[152:155], v[62:65]
	v_mfma_f32_16x16x32_bf16 v[58:61], v[66:69], v[156:159], v[58:61]
	v_mfma_f32_16x16x32_bf16 v[54:57], v[90:93], v[152:155], v[54:57]
	v_mfma_f32_16x16x32_bf16 v[50:53], v[82:85], v[156:159], v[50:53]
	v_mfma_f32_16x16x32_bf16 v[46:49], v[200:203], v[152:155], v[46:49]
	v_mfma_f32_16x16x32_bf16 v[42:45], v[196:199], v[156:159], v[42:45]
	v_mfma_f32_16x16x32_bf16 v[38:41], v[208:211], v[152:155], v[38:41]
	v_mfma_f32_16x16x32_bf16 v[34:37], v[204:207], v[156:159], v[34:37]
	v_mfma_f32_16x16x32_bf16 v[224:227], v[74:77], v[160:163], v[58:61]
	v_mfma_f32_16x16x32_bf16 v[228:231], v[90:93], v[160:163], v[50:53]
	v_mfma_f32_16x16x32_bf16 v[232:235], v[200:203], v[160:163], v[42:45]
	v_mfma_f32_16x16x32_bf16 v[148:151], v[208:211], v[160:163], v[34:37]
	s_setprio 0
	s_setprio 1
	v_mfma_f32_16x16x32_bf16 v[30:33], v[66:69], v[98:101], v[30:33]
	v_mfma_f32_16x16x32_bf16 v[22:25], v[82:85], v[98:101], v[22:25]
	v_mfma_f32_16x16x32_bf16 v[14:17], v[196:199], v[98:101], v[14:17]
	v_mfma_f32_16x16x32_bf16 v[6:9], v[204:207], v[98:101], v[6:9]
	v_mfma_f32_16x16x32_bf16 v[30:33], v[74:77], v[106:109], v[30:33]
	v_mfma_f32_16x16x32_bf16 v[26:29], v[66:69], v[114:117], v[26:29]
	v_mfma_f32_16x16x32_bf16 v[22:25], v[90:93], v[106:109], v[22:25]
	v_mfma_f32_16x16x32_bf16 v[18:21], v[82:85], v[114:117], v[18:21]
	v_mfma_f32_16x16x32_bf16 v[14:17], v[200:203], v[106:109], v[14:17]
	v_mfma_f32_16x16x32_bf16 v[10:13], v[196:199], v[114:117], v[10:13]
	v_mfma_f32_16x16x32_bf16 v[6:9], v[208:211], v[106:109], v[6:9]
	v_mfma_f32_16x16x32_bf16 v[2:5], v[204:207], v[114:117], v[2:5]
	v_mfma_f32_16x16x32_bf16 v[152:155], v[74:77], v[122:125], v[26:29]
	v_mfma_f32_16x16x32_bf16 v[156:159], v[90:93], v[122:125], v[18:21]
	v_mfma_f32_16x16x32_bf16 v[160:163], v[200:203], v[122:125], v[10:13]
	v_mfma_f32_16x16x32_bf16 v[196:199], v[208:211], v[122:125], v[2:5]
	s_setprio 0
	s_barrier
	s_nop 1
	ds_read_b128 v[2:5], v145
	ds_read_b128 v[10:13], v145 offset:1024
	ds_read_b128 v[200:203], v145 offset:2048
	ds_read_b128 v[204:207], v145 offset:3072
	ds_read_b128 v[18:21], v133 offset:32768
	ds_read_b128 v[26:29], v133 offset:33792
	ds_read_b128 v[34:37], v134 offset:32768
	ds_read_b128 v[42:45], v134 offset:33792
	ds_read_b128 v[50:53], v137 offset:32768
	ds_read_b128 v[58:61], v137 offset:33792
	ds_read_b128 v[208:211], v139 offset:32768
	ds_read_b128 v[236:239], v139 offset:33792
	s_waitcnt vmcnt(2)
	s_barrier
	s_waitcnt lgkmcnt(0)
	s_setprio 1
	s_waitcnt lgkmcnt(0)
	v_mfma_f32_16x16x32_bf16 v[66:69], v[18:21], v[2:5], v[126:129]
	v_mfma_f32_16x16x32_bf16 v[122:125], v[26:29], v[10:13], v[66:69]
	v_mfma_f32_16x16x32_bf16 v[66:69], v[18:21], v[200:203], v[140:143]
	v_mfma_f32_16x16x32_bf16 v[114:117], v[26:29], v[204:207], v[66:69]
	v_mfma_f32_16x16x32_bf16 v[66:69], v[34:37], v[2:5], v[118:121]
	v_mfma_f32_16x16x32_bf16 v[106:109], v[42:45], v[10:13], v[66:69]
	v_mfma_f32_16x16x32_bf16 v[66:69], v[34:37], v[200:203], v[212:215]
	v_mfma_f32_16x16x32_bf16 v[98:101], v[42:45], v[204:207], v[66:69]
	v_mfma_f32_16x16x32_bf16 v[66:69], v[50:53], v[2:5], v[110:113]
	v_mfma_f32_16x16x32_bf16 v[90:93], v[58:61], v[10:13], v[66:69]
	v_mfma_f32_16x16x32_bf16 v[66:69], v[50:53], v[200:203], v[216:219]
	v_mfma_f32_16x16x32_bf16 v[82:85], v[58:61], v[204:207], v[66:69]
	v_mfma_f32_16x16x32_bf16 v[66:69], v[208:211], v[2:5], v[102:105]
	v_mfma_f32_16x16x32_bf16 v[74:77], v[236:239], v[10:13], v[66:69]
	v_mfma_f32_16x16x32_bf16 v[66:69], v[208:211], v[200:203], v[220:223]
	v_mfma_f32_16x16x32_bf16 v[66:69], v[236:239], v[204:207], v[66:69]
	s_setprio 0
	s_barrier
; #define LDA(dst, b, h) for (int m = 0; m < 4; ++m) for (int k = 0; k < 2; ++k) \
;     dst[m][k] = *reinterpret_cast<const bf16x8*>((char*)SA(b, h) + lds_byte(wr * 64 + m * 16 + fr, k * 32 + fq * 8))
; #define LDB(dst, b, h) for (int n = 0; n < 2; ++n) for (int k = 0; k < 2; ++k) \
;     dst[n][k] = *reinterpret_cast<const bf16x8*>((char*)SB(b, h) + lds_byte(wc * 32 + n * 16 + fr, k * 32 + fq * 8))
; #define MMA(ai, bj, At, Bt_) do { __builtin_amdgcn_s_setprio(1); \
;     for (int m = 0; m < 4; ++m) for (int n = 0; n < 2; ++n) for (int k = 0; k < 2; ++k) \
;       acc[ai][bj][m][n] = __builtin_amdgcn_mfma_f32_16x16x32_bf16(At[m][k], Bt_[n][k], acc[ai][bj][m][n], 0, 0, 0); \
;     __builtin_amdgcn_s_setprio(0); } while (0)
; #define WAIT_V(n) asm volatile("s_waitcnt vmcnt(" #n ")" ::: "memory")
; #define WAIT_L(n) asm volatile("s_waitcnt lgkmcnt(" #n ")" ::: "memory")
; #define BAR __builtin_amdgcn_s_barrier()
;     ...
;       LDB(B1, 1, 1); WAIT_V(0); BAR; WAIT_L(0); MMA(0, 1, At, B1); BAR;
;       LDA(At, 1, 1); BAR; WAIT_L(0); MMA(1, 0, At, B0); MMA(1, 1, At, B1); BAR; }
;     if (wr == 0) BAR;
	ds_read_b128 v[140:143], v146
	ds_read_b128 v[212:215], v146 offset:1024
	ds_read_b128 v[216:219], v146 offset:2048
	ds_read_b128 v[144:147], v146 offset:3072
	s_waitcnt vmcnt(0)
	s_barrier
	s_waitcnt lgkmcnt(0)
	s_setprio 1
	s_waitcnt lgkmcnt(0)
	v_mfma_f32_16x16x32_bf16 v[94:97], v[18:21], v[140:143], v[94:97]
	v_mfma_f32_16x16x32_bf16 v[18:21], v[18:21], v[216:219], v[164:167]
	v_mfma_f32_16x16x32_bf16 v[118:121], v[26:29], v[144:147], v[18:21]
	v_mfma_f32_16x16x32_bf16 v[18:21], v[34:37], v[140:143], v[86:89]
	v_mfma_f32_16x16x32_bf16 v[110:113], v[42:45], v[212:215], v[18:21]
	v_mfma_f32_16x16x32_bf16 v[18:21], v[34:37], v[216:219], v[184:187]
	v_mfma_f32_16x16x32_bf16 v[102:105], v[42:45], v[144:147], v[18:21]
	v_mfma_f32_16x16x32_bf16 v[18:21], v[50:53], v[140:143], v[78:81]
	v_mfma_f32_16x16x32_bf16 v[126:129], v[26:29], v[212:215], v[94:97]
	v_mfma_f32_16x16x32_bf16 v[94:97], v[58:61], v[212:215], v[18:21]
	v_mfma_f32_16x16x32_bf16 v[18:21], v[50:53], v[216:219], v[188:191]
	v_mfma_f32_16x16x32_bf16 v[86:89], v[58:61], v[144:147], v[18:21]
	v_mfma_f32_16x16x32_bf16 v[18:21], v[208:211], v[140:143], v[70:73]
	v_mfma_f32_16x16x32_bf16 v[78:81], v[236:239], v[212:215], v[18:21]
	v_mfma_f32_16x16x32_bf16 v[18:21], v[208:211], v[216:219], v[192:195]
	v_mfma_f32_16x16x32_bf16 v[70:73], v[236:239], v[144:147], v[18:21]
	s_setprio 0
	s_barrier
	ds_read_b128 v[164:167], v133 offset:49152
	ds_read_b128 v[184:187], v133 offset:50176
	ds_read_b128 v[188:191], v134 offset:49152
	ds_read_b128 v[192:195], v134 offset:50176
	ds_read_b128 v[208:211], v137 offset:49152
	ds_read_b128 v[220:223], v137 offset:50176
	ds_read_b128 v[236:239], v139 offset:49152
	ds_read_b128 v[240:243], v139 offset:50176
	s_barrier
	s_waitcnt lgkmcnt(0)
	s_setprio 1
	s_waitcnt lgkmcnt(0)
	v_mfma_f32_16x16x32_bf16 v[18:21], v[164:167], v[2:5], v[62:65]
	v_mfma_f32_16x16x32_bf16 v[58:61], v[184:187], v[10:13], v[18:21]
	v_mfma_f32_16x16x32_bf16 v[18:21], v[164:167], v[200:203], v[224:227]
	v_mfma_f32_16x16x32_bf16 v[50:53], v[184:187], v[204:207], v[18:21]
	v_mfma_f32_16x16x32_bf16 v[18:21], v[188:191], v[2:5], v[54:57]
	v_mfma_f32_16x16x32_bf16 v[42:45], v[192:195], v[10:13], v[18:21]
	v_mfma_f32_16x16x32_bf16 v[18:21], v[188:191], v[200:203], v[228:231]
	v_mfma_f32_16x16x32_bf16 v[34:37], v[192:195], v[204:207], v[18:21]
	v_mfma_f32_16x16x32_bf16 v[18:21], v[208:211], v[2:5], v[46:49]
	v_mfma_f32_16x16x32_bf16 v[2:5], v[236:239], v[2:5], v[38:41]
	v_mfma_f32_16x16x32_bf16 v[26:29], v[220:223], v[10:13], v[18:21]
	v_mfma_f32_16x16x32_bf16 v[18:21], v[208:211], v[200:203], v[232:235]
	v_mfma_f32_16x16x32_bf16 v[10:13], v[240:243], v[10:13], v[2:5]
	v_mfma_f32_16x16x32_bf16 v[2:5], v[236:239], v[200:203], v[148:151]
	v_mfma_f32_16x16x32_bf16 v[18:21], v[220:223], v[204:207], v[18:21]
	v_mfma_f32_16x16x32_bf16 v[2:5], v[240:243], v[204:207], v[2:5]
	s_setprio 0
	s_setprio 1
	v_mfma_f32_16x16x32_bf16 v[30:33], v[164:167], v[140:143], v[30:33]
	v_mfma_f32_16x16x32_bf16 v[62:65], v[184:187], v[212:215], v[30:33]
	v_mfma_f32_16x16x32_bf16 v[30:33], v[164:167], v[216:219], v[152:155]
	v_mfma_f32_16x16x32_bf16 v[22:25], v[188:191], v[140:143], v[22:25]
	v_mfma_f32_16x16x32_bf16 v[14:17], v[208:211], v[140:143], v[14:17]
	v_mfma_f32_16x16x32_bf16 v[54:57], v[184:187], v[144:147], v[30:33]
	v_mfma_f32_16x16x32_bf16 v[46:49], v[192:195], v[212:215], v[22:25]
	v_mfma_f32_16x16x32_bf16 v[22:25], v[188:191], v[216:219], v[156:159]
	v_mfma_f32_16x16x32_bf16 v[30:33], v[220:223], v[212:215], v[14:17]
	v_mfma_f32_16x16x32_bf16 v[14:17], v[208:211], v[216:219], v[160:163]
	v_mfma_f32_16x16x32_bf16 v[6:9], v[236:239], v[140:143], v[6:9]
	v_mfma_f32_16x16x32_bf16 v[38:41], v[192:195], v[144:147], v[22:25]
	v_mfma_f32_16x16x32_bf16 v[22:25], v[220:223], v[144:147], v[14:17]
	v_mfma_f32_16x16x32_bf16 v[14:17], v[240:243], v[212:215], v[6:9]
	v_mfma_f32_16x16x32_bf16 v[6:9], v[236:239], v[216:219], v[196:199]
	v_mfma_f32_16x16x32_bf16 v[6:9], v[240:243], v[144:147], v[6:9]
	s_setprio 0
	v_readlane_b32 s4, v245, 33
	v_readlane_b32 s5, v245, 34
	s_and_b64 vcc, exec, s[4:5]
	s_barrier
	s_cbranch_vccz .LBB0_158
	s_barrier

; #define LDA(dst, b, h) for (int m = 0; m < 4; ++m) for (int k = 0; k < 2; ++k) \
;     dst[m][k] = *reinterpret_cast<const bf16x8*>((char*)SA(b, h) + lds_byte(wr * 64 + m * 16 + fr, k * 32 + fq * 8))
; #define LDB(dst, b, h) for (int n = 0; n < 2; ++n) for (int k = 0; k < 2; ++k) \
;     dst[n][k] = *reinterpret_cast<const bf16x8*>((char*)SB(b, h) + lds_byte(wc * 32 + n * 16 + fr, k * 32 + fq * 8))
; #define MMA(ai, bj, At, Bt_) do { __builtin_amdgcn_s_setprio(1); \
;     for (int m = 0; m < 4; ++m) for (int n = 0; n < 2; ++n) for (int k = 0; k < 2; ++k) \
;       acc[ai][bj][m][n] = __builtin_amdgcn_mfma_f32_16x16x32_bf16(At[m][k], Bt_[n][k], acc[ai][bj][m][n], 0, 0, 0); \
;     __builtin_amdgcn_s_setprio(0); } while (0)
; #define WAIT_L(n) asm volatile("s_waitcnt lgkmcnt(" #n ")" ::: "memory")
; #define BAR __builtin_amdgcn_s_barrier()
; #define SCHED __builtin_amdgcn_sched_barrier(0)
;     ...
;       LDB(B0, 0, 0); SCHED; LDA(At, 0, 0); STAGE(SA(1, 1), A, brow + HALF, t + 1);
;       WAIT_L(8); BAR; WAIT_L(0); MMA(0, 0, At, B0); BAR; SCHED;
;       LDB(B1, 0, 1); STAGE(SB(0, 0), Bt, bcol, t + 2);
;       BAR; WAIT_L(0); MMA(0, 1, At, B1); BAR;
;       LDA(At, 0, 1); STAGE(SA(0, 0), A, brow, t + 2);
;       BAR; WAIT_L(0); MMA(1, 0, At, B0); BAR; SCHED;
.LBB0_202:
	v_add_u32_e32 v143, s2, v142
	ds_read_b128 v[146:149], v143
	ds_read_b128 v[150:153], v143 offset:1024
	ds_read_b128 v[154:157], v143 offset:2048
	ds_read_b128 v[158:161], v143 offset:3072
	s_add_u32 s66, s50, s16
	s_addc_u32 s67, s51, s17
	s_add_i32 s58, s21, 0xc000
	ds_read_b128 v[162:165], v133
	ds_read_b128 v[184:187], v133 offset:1024
	ds_read_b128 v[188:191], v134
	ds_read_b128 v[192:195], v134 offset:1024
	ds_read_b128 v[196:199], v137
	ds_read_b128 v[200:203], v137 offset:1024
	ds_read_b128 v[204:207], v139
	ds_read_b128 v[208:211], v139 offset:1024
	s_mov_b32 m0, s58
	v_lshl_add_u64 v[144:145], s[66:67], 0, v[0:1]
	s_add_i32 s57, s21, 0xe000
	global_load_lds_dwordx4 v[144:145], off
	v_lshl_add_u64 v[144:145], s[66:67], 0, v[140:141]
	s_mov_b32 m0, s57
	s_nop 0
	global_load_lds_dwordx4 v[144:145], off
	s_waitcnt lgkmcnt(8)
	s_barrier
	s_waitcnt lgkmcnt(0)
	s_waitcnt lgkmcnt(0)
	v_mfma_f32_16x16x32_bf16 v[126:129], v[162:165], v[146:149], v[126:129]
	v_mfma_f32_16x16x32_bf16 v[122:125], v[162:165], v[154:157], v[122:125]
	v_mfma_f32_16x16x32_bf16 v[118:121], v[188:191], v[146:149], v[118:121]
	v_mfma_f32_16x16x32_bf16 v[114:117], v[188:191], v[154:157], v[114:117]
	v_mfma_f32_16x16x32_bf16 v[110:113], v[196:199], v[146:149], v[110:113]
	v_mfma_f32_16x16x32_bf16 v[106:109], v[196:199], v[154:157], v[106:109]
	v_mfma_f32_16x16x32_bf16 v[102:105], v[204:207], v[146:149], v[102:105]
	v_mfma_f32_16x16x32_bf16 v[98:101], v[204:207], v[154:157], v[98:101]
	v_mfma_f32_16x16x32_bf16 v[126:129], v[184:187], v[150:153], v[126:129]
	v_mfma_f32_16x16x32_bf16 v[122:125], v[184:187], v[158:161], v[122:125]
	v_mfma_f32_16x16x32_bf16 v[118:121], v[192:195], v[150:153], v[118:121]
	v_mfma_f32_16x16x32_bf16 v[114:117], v[192:195], v[158:161], v[114:117]
	v_mfma_f32_16x16x32_bf16 v[110:113], v[200:203], v[150:153], v[110:113]
	v_mfma_f32_16x16x32_bf16 v[106:109], v[200:203], v[158:161], v[106:109]
	v_mfma_f32_16x16x32_bf16 v[102:105], v[208:211], v[150:153], v[102:105]
	v_mfma_f32_16x16x32_bf16 v[98:101], v[208:211], v[158:161], v[98:101]
	s_barrier
	s_add_i32 s55, s55, 2
	s_add_u32 s59, s11, s16
	s_addc_u32 s63, s44, s17
	s_add_u32 s66, s59, 0x100
	v_add_u32_e32 v144, s76, v142
	s_addc_u32 s67, s63, 0
	s_mov_b32 m0, s29
	ds_read_b128 v[212:215], v144
	ds_read_b128 v[216:219], v144 offset:1024
	ds_read_b128 v[220:223], v144 offset:2048
	ds_read_b128 v[224:227], v144 offset:3072
	s_nop 0
	v_lshl_add_u64 v[166:167], s[66:67], 0, v[0:1]
	global_load_lds_dwordx4 v[166:167], off
	v_lshl_add_u64 v[166:167], s[66:67], 0, v[140:141]
	s_mov_b32 m0, s30
	s_nop 0
	global_load_lds_dwordx4 v[166:167], off
	s_barrier
	s_waitcnt lgkmcnt(0)
	s_waitcnt lgkmcnt(0)
	v_mfma_f32_16x16x32_bf16 v[94:97], v[162:165], v[212:215], v[94:97]
	v_mfma_f32_16x16x32_bf16 v[90:93], v[162:165], v[220:223], v[90:93]
	v_mfma_f32_16x16x32_bf16 v[86:89], v[188:191], v[212:215], v[86:89]
	v_mfma_f32_16x16x32_bf16 v[82:85], v[188:191], v[220:223], v[82:85]
	v_mfma_f32_16x16x32_bf16 v[78:81], v[196:199], v[212:215], v[78:81]
	v_mfma_f32_16x16x32_bf16 v[74:77], v[196:199], v[220:223], v[74:77]
	v_mfma_f32_16x16x32_bf16 v[70:73], v[204:207], v[212:215], v[70:73]
	v_mfma_f32_16x16x32_bf16 v[66:69], v[204:207], v[220:223], v[66:69]
	v_mfma_f32_16x16x32_bf16 v[94:97], v[184:187], v[216:219], v[94:97]
	v_mfma_f32_16x16x32_bf16 v[90:93], v[184:187], v[224:227], v[90:93]
	v_mfma_f32_16x16x32_bf16 v[86:89], v[192:195], v[216:219], v[86:89]
	v_mfma_f32_16x16x32_bf16 v[82:85], v[192:195], v[224:227], v[82:85]
	v_mfma_f32_16x16x32_bf16 v[78:81], v[200:203], v[216:219], v[78:81]
	v_mfma_f32_16x16x32_bf16 v[74:77], v[200:203], v[224:227], v[74:77]
	v_mfma_f32_16x16x32_bf16 v[70:73], v[208:211], v[216:219], v[70:73]
	v_mfma_f32_16x16x32_bf16 v[66:69], v[208:211], v[224:227], v[66:69]
	s_add_u32 s65, s13, s16
	s_addc_u32 s70, s45, s17
	s_add_u32 s66, s65, 0x100
	s_addc_u32 s67, s70, 0
	s_mov_b32 m0, s21
	s_barrier
	ds_read_b128 v[162:165], v133 offset:16384
	ds_read_b128 v[184:187], v133 offset:17408
	ds_read_b128 v[188:191], v134 offset:16384
	ds_read_b128 v[192:195], v134 offset:17408
	ds_read_b128 v[196:199], v137 offset:16384
	ds_read_b128 v[200:203], v137 offset:17408
	ds_read_b128 v[204:207], v139 offset:16384
	ds_read_b128 v[208:211], v139 offset:17408
	s_nop 0
	v_lshl_add_u64 v[166:167], s[66:67], 0, v[0:1]
	global_load_lds_dwordx4 v[166:167], off
	v_lshl_add_u64 v[166:167], s[66:67], 0, v[140:141]
	s_mov_b32 m0, s31
	s_nop 0
	global_load_lds_dwordx4 v[166:167], off
	s_barrier
	s_waitcnt lgkmcnt(0)
	s_waitcnt lgkmcnt(0)
	v_mfma_f32_16x16x32_bf16 v[62:65], v[162:165], v[146:149], v[62:65]
	v_mfma_f32_16x16x32_bf16 v[58:61], v[162:165], v[154:157], v[58:61]
	v_mfma_f32_16x16x32_bf16 v[54:57], v[188:191], v[146:149], v[54:57]
	v_mfma_f32_16x16x32_bf16 v[50:53], v[188:191], v[154:157], v[50:53]
	v_mfma_f32_16x16x32_bf16 v[46:49], v[196:199], v[146:149], v[46:49]
	v_mfma_f32_16x16x32_bf16 v[42:45], v[196:199], v[154:157], v[42:45]
	v_mfma_f32_16x16x32_bf16 v[38:41], v[204:207], v[146:149], v[38:41]
	v_mfma_f32_16x16x32_bf16 v[34:37], v[204:207], v[154:157], v[34:37]
	v_mfma_f32_16x16x32_bf16 v[62:65], v[184:187], v[150:153], v[62:65]
	v_mfma_f32_16x16x32_bf16 v[58:61], v[184:187], v[158:161], v[58:61]
	v_mfma_f32_16x16x32_bf16 v[54:57], v[192:195], v[150:153], v[54:57]
	v_mfma_f32_16x16x32_bf16 v[50:53], v[192:195], v[158:161], v[50:53]
	v_mfma_f32_16x16x32_bf16 v[46:49], v[200:203], v[150:153], v[46:49]
	v_mfma_f32_16x16x32_bf16 v[42:45], v[200:203], v[158:161], v[42:45]
	v_mfma_f32_16x16x32_bf16 v[38:41], v[208:211], v[150:153], v[38:41]
	v_mfma_f32_16x16x32_bf16 v[34:37], v[208:211], v[158:161], v[34:37]
	s_barrier
; #define LDA(dst, b, h) for (int m = 0; m < 4; ++m) for (int k = 0; k < 2; ++k) \
;     dst[m][k] = *reinterpret_cast<const bf16x8*>((char*)SA(b, h) + lds_byte(wr * 64 + m * 16 + fr, k * 32 + fq * 8))
; #define LDB(dst, b, h) for (int n = 0; n < 2; ++n) for (int k = 0; k < 2; ++k) \
;     dst[n][k] = *reinterpret_cast<const bf16x8*>((char*)SB(b, h) + lds_byte(wc * 32 + n * 16 + fr, k * 32 + fq * 8))
; #define MMA(ai, bj, At, Bt_) do { __builtin_amdgcn_s_setprio(1); \
;     for (int m = 0; m < 4; ++m) for (int n = 0; n < 2; ++n) for (int k = 0; k < 2; ++k) \
;       acc[ai][bj][m][n] = __builtin_amdgcn_mfma_f32_16x16x32_bf16(At[m][k], Bt_[n][k], acc[ai][bj][m][n], 0, 0, 0); \
;     __builtin_amdgcn_s_setprio(0); } while (0)
; #define WAIT_V(n) asm volatile("s_waitcnt vmcnt(" #n ")" ::: "memory")
; #define WAIT_L(n) asm volatile("s_waitcnt lgkmcnt(" #n ")" ::: "memory")
; #define BAR __builtin_amdgcn_s_barrier()
; #define SCHED __builtin_amdgcn_sched_barrier(0)
;     ...
;       STAGE(SB(0, 1), Bt, bcol + HALF, t + 2);
;       WAIT_V(6); BAR; MMA(1, 1, At, B1); BAR;
;       LDB(B0, 1, 0); SCHED; LDA(At, 1, 0); STAGE(SA(0, 1), A, brow + HALF, t + 2);
;       WAIT_L(8); BAR; WAIT_L(0); MMA(0, 0, At, B0); BAR; SCHED;
;       LDB(B1, 1, 1); STAGE(SB(1, 0), Bt, bcol, t + 3);
;       BAR; WAIT_L(0); MMA(0, 1, At, B1); BAR;
;       LDA(At, 1, 1); STAGE(SA(1, 0), A, brow, t + 3);
	s_add_u32 s66, s59, 0x80100
	s_addc_u32 s67, s63, 0
	s_mov_b32 m0, s34
	s_nop 0
	v_lshl_add_u64 v[146:147], s[66:67], 0, v[0:1]
	global_load_lds_dwordx4 v[146:147], off
	v_lshl_add_u64 v[146:147], s[66:67], 0, v[140:141]
	s_mov_b32 m0, s35
	s_nop 0
	global_load_lds_dwordx4 v[146:147], off
	s_waitcnt vmcnt(6)
	s_barrier
	v_mfma_f32_16x16x32_bf16 v[30:33], v[162:165], v[212:215], v[30:33]
	v_mfma_f32_16x16x32_bf16 v[26:29], v[162:165], v[220:223], v[26:29]
	v_mfma_f32_16x16x32_bf16 v[22:25], v[188:191], v[212:215], v[22:25]
	v_mfma_f32_16x16x32_bf16 v[18:21], v[188:191], v[220:223], v[18:21]
	v_mfma_f32_16x16x32_bf16 v[14:17], v[196:199], v[212:215], v[14:17]
	v_mfma_f32_16x16x32_bf16 v[10:13], v[196:199], v[220:223], v[10:13]
	v_mfma_f32_16x16x32_bf16 v[6:9], v[204:207], v[212:215], v[6:9]
	v_mfma_f32_16x16x32_bf16 v[2:5], v[204:207], v[220:223], v[2:5]
	v_mfma_f32_16x16x32_bf16 v[30:33], v[184:187], v[216:219], v[30:33]
	v_mfma_f32_16x16x32_bf16 v[26:29], v[184:187], v[224:227], v[26:29]
	v_mfma_f32_16x16x32_bf16 v[22:25], v[192:195], v[216:219], v[22:25]
	v_mfma_f32_16x16x32_bf16 v[18:21], v[192:195], v[224:227], v[18:21]
	v_mfma_f32_16x16x32_bf16 v[14:17], v[200:203], v[216:219], v[14:17]
	v_mfma_f32_16x16x32_bf16 v[10:13], v[200:203], v[224:227], v[10:13]
	v_mfma_f32_16x16x32_bf16 v[6:9], v[208:211], v[216:219], v[6:9]
	v_mfma_f32_16x16x32_bf16 v[2:5], v[208:211], v[224:227], v[2:5]
	v_add_u32_e32 v145, s77, v142
	s_barrier
	ds_read_b128 v[148:151], v145
	ds_read_b128 v[152:155], v145 offset:1024
	ds_read_b128 v[156:159], v145 offset:2048
	ds_read_b128 v[160:163], v145 offset:3072
	s_add_u32 s66, s65, 0x80100
	s_addc_u32 s67, s70, 0
	s_mov_b32 m0, s37
	ds_read_b128 v[164:167], v133 offset:32768
	ds_read_b128 v[184:187], v133 offset:33792
	ds_read_b128 v[188:191], v134 offset:32768
	ds_read_b128 v[192:195], v134 offset:33792
	ds_read_b128 v[196:199], v137 offset:32768
	ds_read_b128 v[200:203], v137 offset:33792
	ds_read_b128 v[204:207], v139 offset:32768
	ds_read_b128 v[208:211], v139 offset:33792
	s_nop 0
	v_lshl_add_u64 v[146:147], s[66:67], 0, v[0:1]
	global_load_lds_dwordx4 v[146:147], off
	v_lshl_add_u64 v[146:147], s[66:67], 0, v[140:141]
	s_mov_b32 m0, s38
	s_nop 0
	global_load_lds_dwordx4 v[146:147], off
	s_waitcnt lgkmcnt(8)
	s_barrier
	s_waitcnt lgkmcnt(0)
	s_waitcnt lgkmcnt(0)
	v_mfma_f32_16x16x32_bf16 v[126:129], v[164:167], v[148:151], v[126:129]
	v_mfma_f32_16x16x32_bf16 v[122:125], v[164:167], v[156:159], v[122:125]
	v_mfma_f32_16x16x32_bf16 v[118:121], v[188:191], v[148:151], v[118:121]
	v_mfma_f32_16x16x32_bf16 v[114:117], v[188:191], v[156:159], v[114:117]
	v_mfma_f32_16x16x32_bf16 v[110:113], v[196:199], v[148:151], v[110:113]
	v_mfma_f32_16x16x32_bf16 v[106:109], v[196:199], v[156:159], v[106:109]
	v_mfma_f32_16x16x32_bf16 v[102:105], v[204:207], v[148:151], v[102:105]
	v_mfma_f32_16x16x32_bf16 v[98:101], v[204:207], v[156:159], v[98:101]
	v_mfma_f32_16x16x32_bf16 v[126:129], v[184:187], v[152:155], v[126:129]
	v_mfma_f32_16x16x32_bf16 v[122:125], v[184:187], v[160:163], v[122:125]
	v_mfma_f32_16x16x32_bf16 v[118:121], v[192:195], v[152:155], v[118:121]
	v_mfma_f32_16x16x32_bf16 v[114:117], v[192:195], v[160:163], v[114:117]
	v_mfma_f32_16x16x32_bf16 v[110:113], v[200:203], v[152:155], v[110:113]
	v_mfma_f32_16x16x32_bf16 v[106:109], v[200:203], v[160:163], v[106:109]
	v_mfma_f32_16x16x32_bf16 v[102:105], v[208:211], v[152:155], v[102:105]
	v_mfma_f32_16x16x32_bf16 v[98:101], v[208:211], v[160:163], v[98:101]
	s_barrier
	s_add_u32 s66, s59, 0x180
	v_add_u32_e32 v146, s78, v142
	s_addc_u32 s67, s63, 0
	s_mov_b32 m0, s39
	ds_read_b128 v[212:215], v146
	ds_read_b128 v[216:219], v146 offset:1024
	ds_read_b128 v[220:223], v146 offset:2048
	ds_read_b128 v[224:227], v146 offset:3072
	s_nop 0
	v_lshl_add_u64 v[228:229], s[66:67], 0, v[0:1]
	global_load_lds_dwordx4 v[228:229], off
	v_lshl_add_u64 v[228:229], s[66:67], 0, v[140:141]
	s_mov_b32 m0, s40
	s_nop 0
	global_load_lds_dwordx4 v[228:229], off
	s_barrier
	s_waitcnt lgkmcnt(0)
	s_waitcnt lgkmcnt(0)
	v_mfma_f32_16x16x32_bf16 v[94:97], v[164:167], v[212:215], v[94:97]
	v_mfma_f32_16x16x32_bf16 v[90:93], v[164:167], v[220:223], v[90:93]
	v_mfma_f32_16x16x32_bf16 v[86:89], v[188:191], v[212:215], v[86:89]
	v_mfma_f32_16x16x32_bf16 v[82:85], v[188:191], v[220:223], v[82:85]
	v_mfma_f32_16x16x32_bf16 v[78:81], v[196:199], v[212:215], v[78:81]
	v_mfma_f32_16x16x32_bf16 v[74:77], v[196:199], v[220:223], v[74:77]
	v_mfma_f32_16x16x32_bf16 v[70:73], v[204:207], v[212:215], v[70:73]
	v_mfma_f32_16x16x32_bf16 v[66:69], v[204:207], v[220:223], v[66:69]
	v_mfma_f32_16x16x32_bf16 v[94:97], v[184:187], v[216:219], v[94:97]
	v_mfma_f32_16x16x32_bf16 v[90:93], v[184:187], v[224:227], v[90:93]
	v_mfma_f32_16x16x32_bf16 v[86:89], v[192:195], v[216:219], v[86:89]
	v_mfma_f32_16x16x32_bf16 v[82:85], v[192:195], v[224:227], v[82:85]
	v_mfma_f32_16x16x32_bf16 v[78:81], v[200:203], v[216:219], v[78:81]
	v_mfma_f32_16x16x32_bf16 v[74:77], v[200:203], v[224:227], v[74:77]
	v_mfma_f32_16x16x32_bf16 v[70:73], v[208:211], v[216:219], v[70:73]
	v_mfma_f32_16x16x32_bf16 v[66:69], v[208:211], v[224:227], v[66:69]
	s_add_u32 s66, s65, 0x180
	s_addc_u32 s67, s70, 0
	s_mov_b32 m0, s41
	s_barrier
	ds_read_b128 v[164:167], v133 offset:49152
	ds_read_b128 v[184:187], v133 offset:50176
	ds_read_b128 v[188:191], v134 offset:49152
	ds_read_b128 v[192:195], v134 offset:50176
	ds_read_b128 v[196:199], v137 offset:49152
	ds_read_b128 v[200:203], v137 offset:50176
	ds_read_b128 v[204:207], v139 offset:49152
	ds_read_b128 v[208:211], v139 offset:50176
	s_nop 0
	v_lshl_add_u64 v[228:229], s[66:67], 0, v[0:1]
	global_load_lds_dwordx4 v[228:229], off
	v_lshl_add_u64 v[228:229], s[66:67], 0, v[140:141]
	s_mov_b32 m0, s42
	s_nop 0
	global_load_lds_dwordx4 v[228:229], off
	s_barrier
; #define LDA(dst, b, h) for (int m = 0; m < 4; ++m) for (int k = 0; k < 2; ++k) \
;     dst[m][k] = *reinterpret_cast<const bf16x8*>((char*)SA(b, h) + lds_byte(wr * 64 + m * 16 + fr, k * 32 + fq * 8))
; #define LDB(dst, b, h) for (int n = 0; n < 2; ++n) for (int k = 0; k < 2; ++k) \
;     dst[n][k] = *reinterpret_cast<const bf16x8*>((char*)SB(b, h) + lds_byte(wc * 32 + n * 16 + fr, k * 32 + fq * 8))
; #define MMA(ai, bj, At, Bt_) do { __builtin_amdgcn_s_setprio(1); \
;     for (int m = 0; m < 4; ++m) for (int n = 0; n < 2; ++n) for (int k = 0; k < 2; ++k) \
;       acc[ai][bj][m][n] = __builtin_amdgcn_mfma_f32_16x16x32_bf16(At[m][k], Bt_[n][k], acc[ai][bj][m][n], 0, 0, 0); \
;     __builtin_amdgcn_s_setprio(0); } while (0)
; #define WAIT_V(n) asm volatile("s_waitcnt vmcnt(" #n ")" ::: "memory")
; #define WAIT_L(n) asm volatile("s_waitcnt lgkmcnt(" #n ")" ::: "memory")
; #define BAR __builtin_amdgcn_s_barrier()
; #define SCHED __builtin_amdgcn_sched_barrier(0)
;     ...
;       BAR; WAIT_L(0); MMA(1, 0, At, B0); BAR; SCHED;
;       STAGE(SB(1, 1), Bt, bcol + HALF, t + 3);
;       WAIT_V(6); BAR; MMA(1, 1, At, B1); BAR;
;     }
;     { LDB(B0, 0, 0); LDA(At, 0, 0); STAGE(SA(1, 1), A, brow + HALF, nt - 1);
;       BAR; WAIT_L(0); MMA(0, 0, At, B0); BAR;
;       LDB(B1, 0, 1); BAR; WAIT_L(0); MMA(0, 1, At, B1); BAR;
	s_waitcnt lgkmcnt(0)
	s_waitcnt lgkmcnt(0)
	v_mfma_f32_16x16x32_bf16 v[62:65], v[164:167], v[148:151], v[62:65]
	v_mfma_f32_16x16x32_bf16 v[58:61], v[164:167], v[156:159], v[58:61]
	v_mfma_f32_16x16x32_bf16 v[54:57], v[188:191], v[148:151], v[54:57]
	v_mfma_f32_16x16x32_bf16 v[50:53], v[188:191], v[156:159], v[50:53]
	v_mfma_f32_16x16x32_bf16 v[46:49], v[196:199], v[148:151], v[46:49]
	v_mfma_f32_16x16x32_bf16 v[42:45], v[196:199], v[156:159], v[42:45]
	v_mfma_f32_16x16x32_bf16 v[38:41], v[204:207], v[148:151], v[38:41]
	v_mfma_f32_16x16x32_bf16 v[34:37], v[204:207], v[156:159], v[34:37]
	v_mfma_f32_16x16x32_bf16 v[62:65], v[184:187], v[152:155], v[62:65]
	v_mfma_f32_16x16x32_bf16 v[58:61], v[184:187], v[160:163], v[58:61]
	v_mfma_f32_16x16x32_bf16 v[54:57], v[192:195], v[152:155], v[54:57]
	v_mfma_f32_16x16x32_bf16 v[50:53], v[192:195], v[160:163], v[50:53]
	v_mfma_f32_16x16x32_bf16 v[46:49], v[200:203], v[152:155], v[46:49]
	v_mfma_f32_16x16x32_bf16 v[42:45], v[200:203], v[160:163], v[42:45]
	v_mfma_f32_16x16x32_bf16 v[38:41], v[208:211], v[152:155], v[38:41]
	v_mfma_f32_16x16x32_bf16 v[34:37], v[208:211], v[160:163], v[34:37]
	s_barrier
	s_add_u32 s66, s59, 0x80180
	s_addc_u32 s67, s63, 0
	s_mov_b32 m0, s18
	s_nop 0
	v_lshl_add_u64 v[148:149], s[66:67], 0, v[0:1]
	global_load_lds_dwordx4 v[148:149], off
	v_lshl_add_u64 v[148:149], s[66:67], 0, v[140:141]
	s_mov_b32 m0, s19
	s_nop 0
	global_load_lds_dwordx4 v[148:149], off
	s_waitcnt vmcnt(6)
	s_barrier
	v_mfma_f32_16x16x32_bf16 v[30:33], v[164:167], v[212:215], v[30:33]
	v_mfma_f32_16x16x32_bf16 v[26:29], v[164:167], v[220:223], v[26:29]
	v_mfma_f32_16x16x32_bf16 v[22:25], v[188:191], v[212:215], v[22:25]
	v_mfma_f32_16x16x32_bf16 v[18:21], v[188:191], v[220:223], v[18:21]
	v_mfma_f32_16x16x32_bf16 v[14:17], v[196:199], v[212:215], v[14:17]
	v_mfma_f32_16x16x32_bf16 v[10:13], v[196:199], v[220:223], v[10:13]
	v_mfma_f32_16x16x32_bf16 v[6:9], v[204:207], v[212:215], v[6:9]
	v_mfma_f32_16x16x32_bf16 v[2:5], v[204:207], v[220:223], v[2:5]
	v_mfma_f32_16x16x32_bf16 v[30:33], v[184:187], v[216:219], v[30:33]
	v_mfma_f32_16x16x32_bf16 v[26:29], v[184:187], v[224:227], v[26:29]
	v_mfma_f32_16x16x32_bf16 v[22:25], v[192:195], v[216:219], v[22:25]
	v_mfma_f32_16x16x32_bf16 v[18:21], v[192:195], v[224:227], v[18:21]
	v_mfma_f32_16x16x32_bf16 v[14:17], v[200:203], v[216:219], v[14:17]
	v_mfma_f32_16x16x32_bf16 v[10:13], v[200:203], v[224:227], v[10:13]
	v_mfma_f32_16x16x32_bf16 v[6:9], v[208:211], v[216:219], v[6:9]
	v_mfma_f32_16x16x32_bf16 v[2:5], v[208:211], v[224:227], v[2:5]
	s_add_u32 s11, s11, 0x100
	s_addc_u32 s44, s44, 0
	s_add_u32 s13, s13, 0x100
	s_addc_u32 s45, s45, 0
	s_add_u32 s50, s50, 0x100
	s_addc_u32 s51, s51, 0
	s_cmp_ge_u32 s55, s43
	s_barrier
	s_cbranch_scc0 .LBB0_202
	s_add_i32 s11, s48, s20
	s_add_i32 s48, s11, -1
	s_lshl_b64 s[16:17], s[48:49], 7
	s_add_u32 s11, s74, s16
	s_addc_u32 s13, s75, s17
	s_add_u32 s4, s11, s4
	s_addc_u32 s5, s13, s5
	s_mov_b32 m0, s58
	ds_read_b128 v[148:151], v143
	ds_read_b128 v[152:155], v143 offset:1024
	ds_read_b128 v[156:159], v143 offset:2048
	ds_read_b128 v[160:163], v143 offset:3072
	ds_read_b128 v[164:167], v133
	ds_read_b128 v[184:187], v133 offset:1024
	ds_read_b128 v[188:191], v134
	ds_read_b128 v[192:195], v134 offset:1024
	ds_read_b128 v[196:199], v137
	ds_read_b128 v[200:203], v137 offset:1024
	ds_read_b128 v[204:207], v139
	ds_read_b128 v[208:211], v139 offset:1024
	s_nop 0
	v_lshl_add_u64 v[142:143], s[4:5], 0, v[0:1]
	global_load_lds_dwordx4 v[142:143], off
	v_lshl_add_u64 v[140:141], s[4:5], 0, v[140:141]
	s_mov_b32 m0, s57
	s_nop 0
	global_load_lds_dwordx4 v[140:141], off
	s_barrier
	s_waitcnt lgkmcnt(0)
	s_setprio 1
	s_waitcnt lgkmcnt(0)
	v_mfma_f32_16x16x32_bf16 v[126:129], v[164:167], v[148:151], v[126:129]
	v_mfma_f32_16x16x32_bf16 v[122:125], v[164:167], v[156:159], v[122:125]
	v_mfma_f32_16x16x32_bf16 v[118:121], v[188:191], v[148:151], v[118:121]
	v_mfma_f32_16x16x32_bf16 v[110:113], v[196:199], v[148:151], v[110:113]
	v_mfma_f32_16x16x32_bf16 v[106:109], v[196:199], v[156:159], v[106:109]
	v_mfma_f32_16x16x32_bf16 v[102:105], v[204:207], v[148:151], v[102:105]
	v_mfma_f32_16x16x32_bf16 v[98:101], v[204:207], v[156:159], v[98:101]
	v_mfma_f32_16x16x32_bf16 v[126:129], v[184:187], v[152:155], v[126:129]
	v_mfma_f32_16x16x32_bf16 v[122:125], v[184:187], v[160:163], v[122:125]
	v_mfma_f32_16x16x32_bf16 v[118:121], v[192:195], v[152:155], v[118:121]
	v_mfma_f32_16x16x32_bf16 v[114:117], v[188:191], v[156:159], v[114:117]
	v_mfma_f32_16x16x32_bf16 v[110:113], v[200:203], v[152:155], v[110:113]
	v_mfma_f32_16x16x32_bf16 v[106:109], v[200:203], v[160:163], v[106:109]
	v_mfma_f32_16x16x32_bf16 v[102:105], v[208:211], v[152:155], v[102:105]
	v_mfma_f32_16x16x32_bf16 v[98:101], v[208:211], v[160:163], v[98:101]
	v_mfma_f32_16x16x32_bf16 v[140:143], v[192:195], v[160:163], v[114:117]
	s_setprio 0
	s_barrier
	s_nop 0
	ds_read_b128 v[114:117], v144
	ds_read_b128 v[212:215], v144 offset:1024
	ds_read_b128 v[216:219], v144 offset:2048
	ds_read_b128 v[220:223], v144 offset:3072
	s_barrier
; #define LDA(dst, b, h) for (int m = 0; m < 4; ++m) for (int k = 0; k < 2; ++k) \
;     dst[m][k] = *reinterpret_cast<const bf16x8*>((char*)SA(b, h) + lds_byte(wr * 64 + m * 16 + fr, k * 32 + fq * 8))
; #define LDB(dst, b, h) for (int n = 0; n < 2; ++n) for (int k = 0; k < 2; ++k) \
;     dst[n][k] = *reinterpret_cast<const bf16x8*>((char*)SB(b, h) + lds_byte(wc * 32 + n * 16 + fr, k * 32 + fq * 8))
; #define MMA(ai, bj, At, Bt_) do { __builtin_amdgcn_s_setprio(1); \
;     for (int m = 0; m < 4; ++m) for (int n = 0; n < 2; ++n) for (int k = 0; k < 2; ++k) \
;       acc[ai][bj][m][n] = __builtin_amdgcn_mfma_f32_16x16x32_bf16(At[m][k], Bt_[n][k], acc[ai][bj][m][n], 0, 0, 0); \
;     __builtin_amdgcn_s_setprio(0); } while (0)
; #define WAIT_V(n) asm volatile("s_waitcnt vmcnt(" #n ")" ::: "memory")
; #define WAIT_L(n) asm volatile("s_waitcnt lgkmcnt(" #n ")" ::: "memory")
; #define BAR __builtin_amdgcn_s_barrier()
;     ...
;       LDB(B1, 0, 1); BAR; WAIT_L(0); MMA(0, 1, At, B1); BAR;
;       LDA(At, 0, 1); WAIT_V(4); BAR; WAIT_L(0); MMA(1, 0, At, B0); MMA(1, 1, At, B1); BAR; }
;     { LDB(B0, 1, 0); LDA(At, 1, 0); WAIT_V(2); BAR; WAIT_L(0); MMA(0, 0, At, B0); BAR;
	s_waitcnt lgkmcnt(0)
	s_setprio 1
	s_waitcnt lgkmcnt(0)
	v_mfma_f32_16x16x32_bf16 v[90:93], v[164:167], v[216:219], v[90:93]
	v_mfma_f32_16x16x32_bf16 v[86:89], v[188:191], v[114:117], v[86:89]
	v_mfma_f32_16x16x32_bf16 v[94:97], v[164:167], v[114:117], v[94:97]
	v_mfma_f32_16x16x32_bf16 v[90:93], v[184:187], v[220:223], v[90:93]
	v_mfma_f32_16x16x32_bf16 v[86:89], v[192:195], v[212:215], v[86:89]
	v_mfma_f32_16x16x32_bf16 v[82:85], v[188:191], v[216:219], v[82:85]
	v_mfma_f32_16x16x32_bf16 v[78:81], v[196:199], v[114:117], v[78:81]
	v_mfma_f32_16x16x32_bf16 v[74:77], v[196:199], v[216:219], v[74:77]
	v_mfma_f32_16x16x32_bf16 v[70:73], v[204:207], v[114:117], v[70:73]
	v_mfma_f32_16x16x32_bf16 v[66:69], v[204:207], v[216:219], v[66:69]
	v_mfma_f32_16x16x32_bf16 v[224:227], v[184:187], v[212:215], v[94:97]
	v_mfma_f32_16x16x32_bf16 v[164:167], v[192:195], v[220:223], v[82:85]
	v_mfma_f32_16x16x32_bf16 v[184:187], v[200:203], v[212:215], v[78:81]
	v_mfma_f32_16x16x32_bf16 v[188:191], v[200:203], v[220:223], v[74:77]
	v_mfma_f32_16x16x32_bf16 v[192:195], v[208:211], v[212:215], v[70:73]
	v_mfma_f32_16x16x32_bf16 v[196:199], v[208:211], v[220:223], v[66:69]
	s_setprio 0
	s_barrier
	s_nop 0
	ds_read_b128 v[66:69], v133 offset:16384
	ds_read_b128 v[70:73], v133 offset:17408
	ds_read_b128 v[74:77], v134 offset:16384
	ds_read_b128 v[78:81], v134 offset:17408
	ds_read_b128 v[82:85], v137 offset:16384
	ds_read_b128 v[94:97], v137 offset:17408
	ds_read_b128 v[200:203], v139 offset:16384
	ds_read_b128 v[204:207], v139 offset:17408
	s_waitcnt vmcnt(4)
	s_barrier
	s_waitcnt lgkmcnt(0)
	s_setprio 1
	s_waitcnt lgkmcnt(0)
	v_mfma_f32_16x16x32_bf16 v[62:65], v[66:69], v[148:151], v[62:65]
	v_mfma_f32_16x16x32_bf16 v[58:61], v[66:69], v[156:159], v[58:61]
	v_mfma_f32_16x16x32_bf16 v[54:57], v[74:77], v[148:151], v[54:57]
	v_mfma_f32_16x16x32_bf16 v[50:53], v[74:77], v[156:159], v[50:53]
	v_mfma_f32_16x16x32_bf16 v[46:49], v[82:85], v[148:151], v[46:49]
	v_mfma_f32_16x16x32_bf16 v[42:45], v[82:85], v[156:159], v[42:45]
	v_mfma_f32_16x16x32_bf16 v[38:41], v[200:203], v[148:151], v[38:41]
	v_mfma_f32_16x16x32_bf16 v[34:37], v[200:203], v[156:159], v[34:37]
	v_mfma_f32_16x16x32_bf16 v[62:65], v[70:73], v[152:155], v[62:65]
	v_mfma_f32_16x16x32_bf16 v[58:61], v[70:73], v[160:163], v[58:61]
	v_mfma_f32_16x16x32_bf16 v[54:57], v[78:81], v[152:155], v[54:57]
	v_mfma_f32_16x16x32_bf16 v[50:53], v[78:81], v[160:163], v[50:53]
	v_mfma_f32_16x16x32_bf16 v[46:49], v[94:97], v[152:155], v[46:49]
	v_mfma_f32_16x16x32_bf16 v[42:45], v[94:97], v[160:163], v[42:45]
	v_mfma_f32_16x16x32_bf16 v[38:41], v[204:207], v[152:155], v[38:41]
	v_mfma_f32_16x16x32_bf16 v[34:37], v[204:207], v[160:163], v[34:37]
	s_setprio 0
	s_setprio 1
	v_mfma_f32_16x16x32_bf16 v[30:33], v[66:69], v[114:117], v[30:33]
	v_mfma_f32_16x16x32_bf16 v[26:29], v[66:69], v[216:219], v[26:29]
	v_mfma_f32_16x16x32_bf16 v[22:25], v[74:77], v[114:117], v[22:25]
	v_mfma_f32_16x16x32_bf16 v[18:21], v[74:77], v[216:219], v[18:21]
	v_mfma_f32_16x16x32_bf16 v[14:17], v[82:85], v[114:117], v[14:17]
	v_mfma_f32_16x16x32_bf16 v[10:13], v[82:85], v[216:219], v[10:13]
	v_mfma_f32_16x16x32_bf16 v[6:9], v[200:203], v[114:117], v[6:9]
	v_mfma_f32_16x16x32_bf16 v[2:5], v[200:203], v[216:219], v[2:5]
	v_mfma_f32_16x16x32_bf16 v[148:151], v[70:73], v[212:215], v[30:33]
	v_mfma_f32_16x16x32_bf16 v[152:155], v[70:73], v[220:223], v[26:29]
	v_mfma_f32_16x16x32_bf16 v[156:159], v[78:81], v[212:215], v[22:25]
	v_mfma_f32_16x16x32_bf16 v[160:163], v[78:81], v[220:223], v[18:21]
	v_mfma_f32_16x16x32_bf16 v[208:211], v[94:97], v[212:215], v[14:17]
	v_mfma_f32_16x16x32_bf16 v[228:231], v[94:97], v[220:223], v[10:13]
	v_mfma_f32_16x16x32_bf16 v[212:215], v[204:207], v[212:215], v[6:9]
	v_mfma_f32_16x16x32_bf16 v[200:203], v[204:207], v[220:223], v[2:5]
	s_setprio 0
	s_barrier
	ds_read_b128 v[14:17], v145
	ds_read_b128 v[30:33], v145 offset:1024
	ds_read_b128 v[204:207], v145 offset:2048
	ds_read_b128 v[216:219], v145 offset:3072
	ds_read_b128 v[2:5], v133 offset:32768
	ds_read_b128 v[6:9], v133 offset:33792
	ds_read_b128 v[10:13], v134 offset:32768
	ds_read_b128 v[18:21], v134 offset:33792
	ds_read_b128 v[22:25], v137 offset:32768
	ds_read_b128 v[26:29], v137 offset:33792
	ds_read_b128 v[220:223], v139 offset:32768
	ds_read_b128 v[232:235], v139 offset:33792
	s_waitcnt vmcnt(2)
	s_barrier
; #define LDA(dst, b, h) for (int m = 0; m < 4; ++m) for (int k = 0; k < 2; ++k) \
;     dst[m][k] = *reinterpret_cast<const bf16x8*>((char*)SA(b, h) + lds_byte(wr * 64 + m * 16 + fr, k * 32 + fq * 8))
; #define LDB(dst, b, h) for (int n = 0; n < 2; ++n) for (int k = 0; k < 2; ++k) \
;     dst[n][k] = *reinterpret_cast<const bf16x8*>((char*)SB(b, h) + lds_byte(wc * 32 + n * 16 + fr, k * 32 + fq * 8))
; #define MMA(ai, bj, At, Bt_) do { __builtin_amdgcn_s_setprio(1); \
;     for (int m = 0; m < 4; ++m) for (int n = 0; n < 2; ++n) for (int k = 0; k < 2; ++k) \
;       acc[ai][bj][m][n] = __builtin_amdgcn_mfma_f32_16x16x32_bf16(At[m][k], Bt_[n][k], acc[ai][bj][m][n], 0, 0, 0); \
;     __builtin_amdgcn_s_setprio(0); } while (0)
; #define WAIT_V(n) asm volatile("s_waitcnt vmcnt(" #n ")" ::: "memory")
; #define WAIT_L(n) asm volatile("s_waitcnt lgkmcnt(" #n ")" ::: "memory")
; #define BAR __builtin_amdgcn_s_barrier()
;     ...
;     { LDB(B0, 1, 0); LDA(At, 1, 0); WAIT_V(2); BAR; WAIT_L(0); MMA(0, 0, At, B0); BAR;
;       LDB(B1, 1, 1); WAIT_V(0); BAR; WAIT_L(0); MMA(0, 1, At, B1); BAR;
;       LDA(At, 1, 1); BAR; WAIT_L(0); MMA(1, 0, At, B0); MMA(1, 1, At, B1); BAR; }
;     if (wr == 0) BAR;
	s_waitcnt lgkmcnt(0)
	s_setprio 1
	s_waitcnt lgkmcnt(0)
	v_mfma_f32_16x16x32_bf16 v[66:69], v[2:5], v[14:17], v[126:129]
	v_mfma_f32_16x16x32_bf16 v[114:117], v[6:9], v[30:33], v[66:69]
	v_mfma_f32_16x16x32_bf16 v[66:69], v[2:5], v[204:207], v[122:125]
	v_mfma_f32_16x16x32_bf16 v[126:129], v[6:9], v[216:219], v[66:69]
	v_mfma_f32_16x16x32_bf16 v[66:69], v[10:13], v[14:17], v[118:121]
	v_mfma_f32_16x16x32_bf16 v[82:85], v[18:21], v[30:33], v[66:69]
	v_mfma_f32_16x16x32_bf16 v[66:69], v[10:13], v[204:207], v[140:143]
	v_mfma_f32_16x16x32_bf16 v[94:97], v[18:21], v[216:219], v[66:69]
	v_mfma_f32_16x16x32_bf16 v[66:69], v[22:25], v[14:17], v[110:113]
	v_mfma_f32_16x16x32_bf16 v[74:77], v[26:29], v[30:33], v[66:69]
	v_mfma_f32_16x16x32_bf16 v[66:69], v[22:25], v[204:207], v[106:109]
	v_mfma_f32_16x16x32_bf16 v[78:81], v[26:29], v[216:219], v[66:69]
	v_mfma_f32_16x16x32_bf16 v[66:69], v[220:223], v[14:17], v[102:105]
	v_mfma_f32_16x16x32_bf16 v[70:73], v[220:223], v[204:207], v[98:101]
	v_mfma_f32_16x16x32_bf16 v[66:69], v[232:235], v[30:33], v[66:69]
	v_mfma_f32_16x16x32_bf16 v[70:73], v[232:235], v[216:219], v[70:73]
	s_setprio 0
	s_barrier
	ds_read_b128 v[140:143], v146
	ds_read_b128 v[236:239], v146 offset:1024
	ds_read_b128 v[240:243], v146 offset:2048
	ds_read_b128 v[144:147], v146 offset:3072
	s_waitcnt vmcnt(0)
	s_barrier
	s_waitcnt lgkmcnt(0)
	s_setprio 1
	s_waitcnt lgkmcnt(0)
	v_mfma_f32_16x16x32_bf16 v[98:101], v[2:5], v[140:143], v[224:227]
	v_mfma_f32_16x16x32_bf16 v[2:5], v[2:5], v[240:243], v[90:93]
	v_mfma_f32_16x16x32_bf16 v[118:121], v[6:9], v[144:147], v[2:5]
	v_mfma_f32_16x16x32_bf16 v[2:5], v[10:13], v[140:143], v[86:89]
	v_mfma_f32_16x16x32_bf16 v[102:105], v[18:21], v[236:239], v[2:5]
	v_mfma_f32_16x16x32_bf16 v[2:5], v[10:13], v[240:243], v[164:167]
	v_mfma_f32_16x16x32_bf16 v[122:125], v[18:21], v[144:147], v[2:5]
	v_mfma_f32_16x16x32_bf16 v[2:5], v[22:25], v[140:143], v[184:187]
	v_mfma_f32_16x16x32_bf16 v[90:93], v[26:29], v[236:239], v[2:5]
	v_mfma_f32_16x16x32_bf16 v[2:5], v[22:25], v[240:243], v[188:191]
	v_mfma_f32_16x16x32_bf16 v[110:113], v[26:29], v[144:147], v[2:5]
	v_mfma_f32_16x16x32_bf16 v[2:5], v[220:223], v[140:143], v[192:195]
	v_mfma_f32_16x16x32_bf16 v[86:89], v[232:235], v[236:239], v[2:5]
	v_mfma_f32_16x16x32_bf16 v[2:5], v[220:223], v[240:243], v[196:199]
	v_mfma_f32_16x16x32_bf16 v[98:101], v[6:9], v[236:239], v[98:101]
	v_mfma_f32_16x16x32_bf16 v[106:109], v[232:235], v[144:147], v[2:5]
	s_setprio 0
	s_barrier
	ds_read_b128 v[164:167], v133 offset:49152
	ds_read_b128 v[184:187], v133 offset:50176
	ds_read_b128 v[188:191], v134 offset:49152
	ds_read_b128 v[192:195], v134 offset:50176
	ds_read_b128 v[196:199], v137 offset:49152
	ds_read_b128 v[220:223], v137 offset:50176
	ds_read_b128 v[224:227], v139 offset:49152
	ds_read_b128 v[232:235], v139 offset:50176
	s_barrier
	s_waitcnt lgkmcnt(0)
	s_setprio 1
	s_waitcnt lgkmcnt(0)
	v_mfma_f32_16x16x32_bf16 v[6:9], v[164:167], v[204:207], v[58:61]
	v_mfma_f32_16x16x32_bf16 v[10:13], v[188:191], v[204:207], v[50:53]
	v_mfma_f32_16x16x32_bf16 v[2:5], v[164:167], v[14:17], v[62:65]
	v_mfma_f32_16x16x32_bf16 v[18:21], v[184:187], v[216:219], v[6:9]
	v_mfma_f32_16x16x32_bf16 v[6:9], v[188:191], v[14:17], v[54:57]
	v_mfma_f32_16x16x32_bf16 v[22:25], v[192:195], v[216:219], v[10:13]
	v_mfma_f32_16x16x32_bf16 v[10:13], v[196:199], v[14:17], v[46:49]
	v_mfma_f32_16x16x32_bf16 v[14:17], v[224:227], v[14:17], v[38:41]
	v_mfma_f32_16x16x32_bf16 v[2:5], v[184:187], v[30:33], v[2:5]
	v_mfma_f32_16x16x32_bf16 v[6:9], v[192:195], v[30:33], v[6:9]
	v_mfma_f32_16x16x32_bf16 v[10:13], v[220:223], v[30:33], v[10:13]
	v_mfma_f32_16x16x32_bf16 v[26:29], v[196:199], v[204:207], v[42:45]
	v_mfma_f32_16x16x32_bf16 v[14:17], v[232:235], v[30:33], v[14:17]
	v_mfma_f32_16x16x32_bf16 v[30:33], v[224:227], v[204:207], v[34:37]
	v_mfma_f32_16x16x32_bf16 v[26:29], v[220:223], v[216:219], v[26:29]
	v_mfma_f32_16x16x32_bf16 v[30:33], v[232:235], v[216:219], v[30:33]
	s_setprio 0
	s_setprio 1
	v_mfma_f32_16x16x32_bf16 v[38:41], v[164:167], v[240:243], v[152:155]
	v_mfma_f32_16x16x32_bf16 v[42:45], v[188:191], v[240:243], v[160:163]
	v_mfma_f32_16x16x32_bf16 v[46:49], v[196:199], v[240:243], v[228:231]
	v_mfma_f32_16x16x32_bf16 v[34:37], v[164:167], v[140:143], v[148:151]
	v_mfma_f32_16x16x32_bf16 v[50:53], v[184:187], v[144:147], v[38:41]
	v_mfma_f32_16x16x32_bf16 v[38:41], v[188:191], v[140:143], v[156:159]
	v_mfma_f32_16x16x32_bf16 v[54:57], v[192:195], v[144:147], v[42:45]
	v_mfma_f32_16x16x32_bf16 v[42:45], v[196:199], v[140:143], v[208:211]
	v_mfma_f32_16x16x32_bf16 v[58:61], v[220:223], v[144:147], v[46:49]
	v_mfma_f32_16x16x32_bf16 v[46:49], v[224:227], v[140:143], v[212:215]
	v_mfma_f32_16x16x32_bf16 v[62:65], v[224:227], v[240:243], v[200:203]
	v_mfma_f32_16x16x32_bf16 v[34:37], v[184:187], v[236:239], v[34:37]
	v_mfma_f32_16x16x32_bf16 v[38:41], v[192:195], v[236:239], v[38:41]
	v_mfma_f32_16x16x32_bf16 v[42:45], v[220:223], v[236:239], v[42:45]
	v_mfma_f32_16x16x32_bf16 v[46:49], v[232:235], v[236:239], v[46:49]
	v_mfma_f32_16x16x32_bf16 v[62:65], v[232:235], v[144:147], v[62:65]
	s_setprio 0
	v_readlane_b32 s4, v245, 33
	v_readlane_b32 s5, v245, 34
	s_and_b64 vcc, exec, s[4:5]
	s_barrier
	s_cbranch_vccz .LBB0_205
	s_barrier

; #define LDA(dst, b, h) for (int m = 0; m < 4; ++m) for (int k = 0; k < 2; ++k) \
;     dst[m][k] = *reinterpret_cast<const bf16x8*>((char*)SA(b, h) + lds_byte(wr * 64 + m * 16 + fr, k * 32 + fq * 8))
; #define LDB(dst, b, h) for (int n = 0; n < 2; ++n) for (int k = 0; k < 2; ++k) \
;     dst[n][k] = *reinterpret_cast<const bf16x8*>((char*)SB(b, h) + lds_byte(wc * 32 + n * 16 + fr, k * 32 + fq * 8))
; #define MMA(ai, bj, At, Bt_) do { __builtin_amdgcn_s_setprio(1); \
;     for (int m = 0; m < 4; ++m) for (int n = 0; n < 2; ++n) for (int k = 0; k < 2; ++k) \
;       acc[ai][bj][m][n] = __builtin_amdgcn_mfma_f32_16x16x32_bf16(At[m][k], Bt_[n][k], acc[ai][bj][m][n], 0, 0, 0); \
;     __builtin_amdgcn_s_setprio(0); } while (0)
; #define WAIT_L(n) asm volatile("s_waitcnt lgkmcnt(" #n ")" ::: "memory")
; #define BAR __builtin_amdgcn_s_barrier()
; #define SCHED __builtin_amdgcn_sched_barrier(0)
;     ...
;       LDB(B0, 0, 0); SCHED; LDA(At, 0, 0); STAGE(SA(1, 1), A, brow + HALF, t + 1);
;       WAIT_L(8); BAR; WAIT_L(0); MMA(0, 0, At, B0); BAR; SCHED;
;       LDB(B1, 0, 1); STAGE(SB(0, 0), Bt, bcol, t + 2);
;       BAR; WAIT_L(0); MMA(0, 1, At, B1); BAR;
;       LDA(At, 0, 1); STAGE(SA(0, 0), A, brow, t + 2);
;       BAR; WAIT_L(0); MMA(1, 0, At, B0); BAR; SCHED;
.LBB0_418:
	v_add_u32_e32 v143, s2, v142
	ds_read_b128 v[146:149], v143
	ds_read_b128 v[150:153], v143 offset:1024
	ds_read_b128 v[154:157], v143 offset:2048
	ds_read_b128 v[158:161], v143 offset:3072
	s_add_u32 s42, s30, s6
	s_addc_u32 s43, s31, s7
	s_add_u32 s44, s42, 0x80080
	s_addc_u32 s45, s43, 0
	s_add_i32 s41, s15, 0xc000
	ds_read_b128 v[162:165], v133
	ds_read_b128 v[184:187], v133 offset:1024
	ds_read_b128 v[188:191], v134
	ds_read_b128 v[192:195], v134 offset:1024
	ds_read_b128 v[196:199], v137
	ds_read_b128 v[200:203], v137 offset:1024
	ds_read_b128 v[204:207], v139
	ds_read_b128 v[208:211], v139 offset:1024
	s_mov_b32 m0, s41
	v_lshl_add_u64 v[144:145], s[44:45], 0, v[0:1]
	s_add_i32 s37, s15, 0xe000
	global_load_lds_dwordx4 v[144:145], off
	v_lshl_add_u64 v[144:145], s[44:45], 0, v[140:141]
	s_mov_b32 m0, s37
	s_nop 0
	global_load_lds_dwordx4 v[144:145], off
	s_waitcnt lgkmcnt(8)
	s_barrier
	s_waitcnt lgkmcnt(0)
	s_waitcnt lgkmcnt(0)
	v_mfma_f32_16x16x32_bf16 v[126:129], v[162:165], v[146:149], v[126:129]
	v_mfma_f32_16x16x32_bf16 v[122:125], v[162:165], v[154:157], v[122:125]
	v_mfma_f32_16x16x32_bf16 v[118:121], v[188:191], v[146:149], v[118:121]
	v_mfma_f32_16x16x32_bf16 v[114:117], v[188:191], v[154:157], v[114:117]
	v_mfma_f32_16x16x32_bf16 v[110:113], v[196:199], v[146:149], v[110:113]
	v_mfma_f32_16x16x32_bf16 v[106:109], v[196:199], v[154:157], v[106:109]
	v_mfma_f32_16x16x32_bf16 v[102:105], v[204:207], v[146:149], v[102:105]
	v_mfma_f32_16x16x32_bf16 v[98:101], v[204:207], v[154:157], v[98:101]
	v_mfma_f32_16x16x32_bf16 v[126:129], v[184:187], v[150:153], v[126:129]
	v_mfma_f32_16x16x32_bf16 v[122:125], v[184:187], v[158:161], v[122:125]
	v_mfma_f32_16x16x32_bf16 v[118:121], v[192:195], v[150:153], v[118:121]
	v_mfma_f32_16x16x32_bf16 v[114:117], v[192:195], v[158:161], v[114:117]
	v_mfma_f32_16x16x32_bf16 v[110:113], v[200:203], v[150:153], v[110:113]
	v_mfma_f32_16x16x32_bf16 v[106:109], v[200:203], v[158:161], v[106:109]
	v_mfma_f32_16x16x32_bf16 v[102:105], v[208:211], v[150:153], v[102:105]
	v_mfma_f32_16x16x32_bf16 v[98:101], v[208:211], v[158:161], v[98:101]
	s_barrier
	s_add_u32 s44, s34, s6
	s_addc_u32 s45, s35, s7
	s_add_u32 s50, s44, 0x100
	v_add_u32_e32 v144, s76, v142
	s_addc_u32 s51, s45, 0
	s_mov_b32 m0, s23
	ds_read_b128 v[212:215], v144
	ds_read_b128 v[216:219], v144 offset:1024
	ds_read_b128 v[220:223], v144 offset:2048
	ds_read_b128 v[224:227], v144 offset:3072
	s_nop 0
	v_lshl_add_u64 v[166:167], s[50:51], 0, v[0:1]
	global_load_lds_dwordx4 v[166:167], off
	v_lshl_add_u64 v[166:167], s[50:51], 0, v[140:141]
	s_mov_b32 m0, s26
	s_nop 0
	global_load_lds_dwordx4 v[166:167], off
	s_barrier
	s_waitcnt lgkmcnt(0)
	s_waitcnt lgkmcnt(0)
	v_mfma_f32_16x16x32_bf16 v[94:97], v[162:165], v[212:215], v[94:97]
	v_mfma_f32_16x16x32_bf16 v[90:93], v[162:165], v[220:223], v[90:93]
	v_mfma_f32_16x16x32_bf16 v[86:89], v[188:191], v[212:215], v[86:89]
	v_mfma_f32_16x16x32_bf16 v[82:85], v[188:191], v[220:223], v[82:85]
	v_mfma_f32_16x16x32_bf16 v[78:81], v[196:199], v[212:215], v[78:81]
	v_mfma_f32_16x16x32_bf16 v[74:77], v[196:199], v[220:223], v[74:77]
	v_mfma_f32_16x16x32_bf16 v[70:73], v[204:207], v[212:215], v[70:73]
	v_mfma_f32_16x16x32_bf16 v[66:69], v[204:207], v[220:223], v[66:69]
	v_mfma_f32_16x16x32_bf16 v[94:97], v[184:187], v[216:219], v[94:97]
	v_mfma_f32_16x16x32_bf16 v[90:93], v[184:187], v[224:227], v[90:93]
	v_mfma_f32_16x16x32_bf16 v[86:89], v[192:195], v[216:219], v[86:89]
	v_mfma_f32_16x16x32_bf16 v[82:85], v[192:195], v[224:227], v[82:85]
	v_mfma_f32_16x16x32_bf16 v[78:81], v[200:203], v[216:219], v[78:81]
	v_mfma_f32_16x16x32_bf16 v[74:77], v[200:203], v[224:227], v[74:77]
	v_mfma_f32_16x16x32_bf16 v[70:73], v[208:211], v[216:219], v[70:73]
	v_mfma_f32_16x16x32_bf16 v[66:69], v[208:211], v[224:227], v[66:69]
	s_add_u32 s50, s42, 0x100
	s_addc_u32 s51, s43, 0
	s_mov_b32 m0, s15
	s_barrier
	ds_read_b128 v[162:165], v133 offset:16384
	ds_read_b128 v[184:187], v133 offset:17408
	ds_read_b128 v[188:191], v134 offset:16384
	ds_read_b128 v[192:195], v134 offset:17408
	ds_read_b128 v[196:199], v137 offset:16384
	ds_read_b128 v[200:203], v137 offset:17408
	ds_read_b128 v[204:207], v139 offset:16384
	ds_read_b128 v[208:211], v139 offset:17408
	s_nop 0
	v_lshl_add_u64 v[166:167], s[50:51], 0, v[0:1]
	global_load_lds_dwordx4 v[166:167], off
	v_lshl_add_u64 v[166:167], s[50:51], 0, v[140:141]
	s_mov_b32 m0, s25
	s_nop 0
	global_load_lds_dwordx4 v[166:167], off
	s_barrier
	s_waitcnt lgkmcnt(0)
	s_waitcnt lgkmcnt(0)
	v_mfma_f32_16x16x32_bf16 v[62:65], v[162:165], v[146:149], v[62:65]
	v_mfma_f32_16x16x32_bf16 v[58:61], v[162:165], v[154:157], v[58:61]
	v_mfma_f32_16x16x32_bf16 v[54:57], v[188:191], v[146:149], v[54:57]
	v_mfma_f32_16x16x32_bf16 v[50:53], v[188:191], v[154:157], v[50:53]
	v_mfma_f32_16x16x32_bf16 v[46:49], v[196:199], v[146:149], v[46:49]
	v_mfma_f32_16x16x32_bf16 v[42:45], v[196:199], v[154:157], v[42:45]
	v_mfma_f32_16x16x32_bf16 v[38:41], v[204:207], v[146:149], v[38:41]
	v_mfma_f32_16x16x32_bf16 v[34:37], v[204:207], v[154:157], v[34:37]
	v_mfma_f32_16x16x32_bf16 v[62:65], v[184:187], v[150:153], v[62:65]
	v_mfma_f32_16x16x32_bf16 v[58:61], v[184:187], v[158:161], v[58:61]
	v_mfma_f32_16x16x32_bf16 v[54:57], v[192:195], v[150:153], v[54:57]
	v_mfma_f32_16x16x32_bf16 v[50:53], v[192:195], v[158:161], v[50:53]
	v_mfma_f32_16x16x32_bf16 v[46:49], v[200:203], v[150:153], v[46:49]
	v_mfma_f32_16x16x32_bf16 v[42:45], v[200:203], v[158:161], v[42:45]
	v_mfma_f32_16x16x32_bf16 v[38:41], v[208:211], v[150:153], v[38:41]
	v_mfma_f32_16x16x32_bf16 v[34:37], v[208:211], v[158:161], v[34:37]
	s_barrier
; #define LDA(dst, b, h) for (int m = 0; m < 4; ++m) for (int k = 0; k < 2; ++k) \
;     dst[m][k] = *reinterpret_cast<const bf16x8*>((char*)SA(b, h) + lds_byte(wr * 64 + m * 16 + fr, k * 32 + fq * 8))
; #define LDB(dst, b, h) for (int n = 0; n < 2; ++n) for (int k = 0; k < 2; ++k) \
;     dst[n][k] = *reinterpret_cast<const bf16x8*>((char*)SB(b, h) + lds_byte(wc * 32 + n * 16 + fr, k * 32 + fq * 8))
; #define MMA(ai, bj, At, Bt_) do { __builtin_amdgcn_s_setprio(1); \
;     for (int m = 0; m < 4; ++m) for (int n = 0; n < 2; ++n) for (int k = 0; k < 2; ++k) \
;       acc[ai][bj][m][n] = __builtin_amdgcn_mfma_f32_16x16x32_bf16(At[m][k], Bt_[n][k], acc[ai][bj][m][n], 0, 0, 0); \
;     __builtin_amdgcn_s_setprio(0); } while (0)
; #define WAIT_V(n) asm volatile("s_waitcnt vmcnt(" #n ")" ::: "memory")
; #define WAIT_L(n) asm volatile("s_waitcnt lgkmcnt(" #n ")" ::: "memory")
; #define BAR __builtin_amdgcn_s_barrier()
; #define SCHED __builtin_amdgcn_sched_barrier(0)
;     ...
;       STAGE(SB(0, 1), Bt, bcol + HALF, t + 2);
;       WAIT_V(6); BAR; MMA(1, 1, At, B1); BAR;
;       LDB(B0, 1, 0); SCHED; LDA(At, 1, 0); STAGE(SA(0, 1), A, brow + HALF, t + 2);
;       WAIT_L(8); BAR; WAIT_L(0); MMA(0, 0, At, B0); BAR; SCHED;
;       LDB(B1, 1, 1); STAGE(SB(1, 0), Bt, bcol, t + 3);
;       BAR; WAIT_L(0); MMA(0, 1, At, B1); BAR;
;       LDA(At, 1, 1); STAGE(SA(1, 0), A, brow, t + 3);
	s_add_u32 s50, s44, 0x80100
	s_addc_u32 s51, s45, 0
	s_mov_b32 m0, s27
	s_nop 0
	v_lshl_add_u64 v[146:147], s[50:51], 0, v[0:1]
	global_load_lds_dwordx4 v[146:147], off
	v_lshl_add_u64 v[146:147], s[50:51], 0, v[140:141]
	s_mov_b32 m0, s28
	s_nop 0
	global_load_lds_dwordx4 v[146:147], off
	s_waitcnt vmcnt(6)
	s_barrier
	v_mfma_f32_16x16x32_bf16 v[30:33], v[162:165], v[212:215], v[30:33]
	v_mfma_f32_16x16x32_bf16 v[26:29], v[162:165], v[220:223], v[26:29]
	v_mfma_f32_16x16x32_bf16 v[22:25], v[188:191], v[212:215], v[22:25]
	v_mfma_f32_16x16x32_bf16 v[18:21], v[188:191], v[220:223], v[18:21]
	v_mfma_f32_16x16x32_bf16 v[14:17], v[196:199], v[212:215], v[14:17]
	v_mfma_f32_16x16x32_bf16 v[10:13], v[196:199], v[220:223], v[10:13]
	v_mfma_f32_16x16x32_bf16 v[6:9], v[204:207], v[212:215], v[6:9]
	v_mfma_f32_16x16x32_bf16 v[2:5], v[204:207], v[220:223], v[2:5]
	v_mfma_f32_16x16x32_bf16 v[30:33], v[184:187], v[216:219], v[30:33]
	v_mfma_f32_16x16x32_bf16 v[26:29], v[184:187], v[224:227], v[26:29]
	v_mfma_f32_16x16x32_bf16 v[22:25], v[192:195], v[216:219], v[22:25]
	v_mfma_f32_16x16x32_bf16 v[18:21], v[192:195], v[224:227], v[18:21]
	v_mfma_f32_16x16x32_bf16 v[14:17], v[200:203], v[216:219], v[14:17]
	v_mfma_f32_16x16x32_bf16 v[10:13], v[200:203], v[224:227], v[10:13]
	v_mfma_f32_16x16x32_bf16 v[6:9], v[208:211], v[216:219], v[6:9]
	v_mfma_f32_16x16x32_bf16 v[2:5], v[208:211], v[224:227], v[2:5]
	v_add_u32_e32 v145, s77, v142
	s_barrier
	ds_read_b128 v[148:151], v145
	ds_read_b128 v[152:155], v145 offset:1024
	ds_read_b128 v[156:159], v145 offset:2048
	ds_read_b128 v[160:163], v145 offset:3072
	s_add_u32 s50, s42, 0x80100
	s_addc_u32 s51, s43, 0
	s_mov_b32 m0, s17
	ds_read_b128 v[164:167], v133 offset:32768
	ds_read_b128 v[184:187], v133 offset:33792
	ds_read_b128 v[188:191], v134 offset:32768
	ds_read_b128 v[192:195], v134 offset:33792
	ds_read_b128 v[196:199], v137 offset:32768
	ds_read_b128 v[200:203], v137 offset:33792
	ds_read_b128 v[204:207], v139 offset:32768
	ds_read_b128 v[208:211], v139 offset:33792
	s_nop 0
	v_lshl_add_u64 v[146:147], s[50:51], 0, v[0:1]
	global_load_lds_dwordx4 v[146:147], off
	v_lshl_add_u64 v[146:147], s[50:51], 0, v[140:141]
	s_mov_b32 m0, s29
	s_nop 0
	global_load_lds_dwordx4 v[146:147], off
	s_waitcnt lgkmcnt(8)
	s_barrier
	s_waitcnt lgkmcnt(0)
	s_waitcnt lgkmcnt(0)
	v_mfma_f32_16x16x32_bf16 v[126:129], v[164:167], v[148:151], v[126:129]
	v_mfma_f32_16x16x32_bf16 v[122:125], v[164:167], v[156:159], v[122:125]
	v_mfma_f32_16x16x32_bf16 v[118:121], v[188:191], v[148:151], v[118:121]
	v_mfma_f32_16x16x32_bf16 v[114:117], v[188:191], v[156:159], v[114:117]
	v_mfma_f32_16x16x32_bf16 v[110:113], v[196:199], v[148:151], v[110:113]
	v_mfma_f32_16x16x32_bf16 v[106:109], v[196:199], v[156:159], v[106:109]
	v_mfma_f32_16x16x32_bf16 v[102:105], v[204:207], v[148:151], v[102:105]
	v_mfma_f32_16x16x32_bf16 v[98:101], v[204:207], v[156:159], v[98:101]
	v_mfma_f32_16x16x32_bf16 v[126:129], v[184:187], v[152:155], v[126:129]
	v_mfma_f32_16x16x32_bf16 v[122:125], v[184:187], v[160:163], v[122:125]
	v_mfma_f32_16x16x32_bf16 v[118:121], v[192:195], v[152:155], v[118:121]
	v_mfma_f32_16x16x32_bf16 v[114:117], v[192:195], v[160:163], v[114:117]
	v_mfma_f32_16x16x32_bf16 v[110:113], v[200:203], v[152:155], v[110:113]
	v_mfma_f32_16x16x32_bf16 v[106:109], v[200:203], v[160:163], v[106:109]
	v_mfma_f32_16x16x32_bf16 v[102:105], v[208:211], v[152:155], v[102:105]
	v_mfma_f32_16x16x32_bf16 v[98:101], v[208:211], v[160:163], v[98:101]
	s_barrier
	s_add_u32 s50, s44, 0x180
	v_add_u32_e32 v146, s78, v142
	s_addc_u32 s51, s45, 0
	s_mov_b32 m0, s8
	ds_read_b128 v[212:215], v146
	ds_read_b128 v[216:219], v146 offset:1024
	ds_read_b128 v[220:223], v146 offset:2048
	ds_read_b128 v[224:227], v146 offset:3072
	s_nop 0
	v_lshl_add_u64 v[228:229], s[50:51], 0, v[0:1]
	global_load_lds_dwordx4 v[228:229], off
	v_lshl_add_u64 v[228:229], s[50:51], 0, v[140:141]
	s_mov_b32 m0, s9
	s_nop 0
	global_load_lds_dwordx4 v[228:229], off
	s_barrier
	s_waitcnt lgkmcnt(0)
	s_waitcnt lgkmcnt(0)
	v_mfma_f32_16x16x32_bf16 v[94:97], v[164:167], v[212:215], v[94:97]
	v_mfma_f32_16x16x32_bf16 v[90:93], v[164:167], v[220:223], v[90:93]
	v_mfma_f32_16x16x32_bf16 v[86:89], v[188:191], v[212:215], v[86:89]
	v_mfma_f32_16x16x32_bf16 v[82:85], v[188:191], v[220:223], v[82:85]
	v_mfma_f32_16x16x32_bf16 v[78:81], v[196:199], v[212:215], v[78:81]
	v_mfma_f32_16x16x32_bf16 v[74:77], v[196:199], v[220:223], v[74:77]
	v_mfma_f32_16x16x32_bf16 v[70:73], v[204:207], v[212:215], v[70:73]
	v_mfma_f32_16x16x32_bf16 v[66:69], v[204:207], v[220:223], v[66:69]
	v_mfma_f32_16x16x32_bf16 v[94:97], v[184:187], v[216:219], v[94:97]
	v_mfma_f32_16x16x32_bf16 v[90:93], v[184:187], v[224:227], v[90:93]
	v_mfma_f32_16x16x32_bf16 v[86:89], v[192:195], v[216:219], v[86:89]
	v_mfma_f32_16x16x32_bf16 v[82:85], v[192:195], v[224:227], v[82:85]
	v_mfma_f32_16x16x32_bf16 v[78:81], v[200:203], v[216:219], v[78:81]
	v_mfma_f32_16x16x32_bf16 v[74:77], v[200:203], v[224:227], v[74:77]
	v_mfma_f32_16x16x32_bf16 v[70:73], v[208:211], v[216:219], v[70:73]
	v_mfma_f32_16x16x32_bf16 v[66:69], v[208:211], v[224:227], v[66:69]
	s_add_u32 s42, s42, 0x180
	s_addc_u32 s43, s43, 0
	s_mov_b32 m0, s18
	s_barrier
	ds_read_b128 v[164:167], v133 offset:49152
	ds_read_b128 v[184:187], v133 offset:50176
	ds_read_b128 v[188:191], v134 offset:49152
	ds_read_b128 v[192:195], v134 offset:50176
	ds_read_b128 v[196:199], v137 offset:49152
	ds_read_b128 v[200:203], v137 offset:50176
	ds_read_b128 v[204:207], v139 offset:49152
	ds_read_b128 v[208:211], v139 offset:50176
	s_nop 0
	v_lshl_add_u64 v[228:229], s[42:43], 0, v[0:1]
	global_load_lds_dwordx4 v[228:229], off
	v_lshl_add_u64 v[228:229], s[42:43], 0, v[140:141]
	s_mov_b32 m0, s19
	s_nop 0
	global_load_lds_dwordx4 v[228:229], off
	s_barrier
; #define LDA(dst, b, h) for (int m = 0; m < 4; ++m) for (int k = 0; k < 2; ++k) \
;     dst[m][k] = *reinterpret_cast<const bf16x8*>((char*)SA(b, h) + lds_byte(wr * 64 + m * 16 + fr, k * 32 + fq * 8))
; #define LDB(dst, b, h) for (int n = 0; n < 2; ++n) for (int k = 0; k < 2; ++k) \
;     dst[n][k] = *reinterpret_cast<const bf16x8*>((char*)SB(b, h) + lds_byte(wc * 32 + n * 16 + fr, k * 32 + fq * 8))
; #define MMA(ai, bj, At, Bt_) do { __builtin_amdgcn_s_setprio(1); \
;     for (int m = 0; m < 4; ++m) for (int n = 0; n < 2; ++n) for (int k = 0; k < 2; ++k) \
;       acc[ai][bj][m][n] = __builtin_amdgcn_mfma_f32_16x16x32_bf16(At[m][k], Bt_[n][k], acc[ai][bj][m][n], 0, 0, 0); \
;     __builtin_amdgcn_s_setprio(0); } while (0)
; #define WAIT_V(n) asm volatile("s_waitcnt vmcnt(" #n ")" ::: "memory")
; #define WAIT_L(n) asm volatile("s_waitcnt lgkmcnt(" #n ")" ::: "memory")
; #define BAR __builtin_amdgcn_s_barrier()
; #define SCHED __builtin_amdgcn_sched_barrier(0)
;     ...
;       BAR; WAIT_L(0); MMA(1, 0, At, B0); BAR; SCHED;
;       STAGE(SB(1, 1), Bt, bcol + HALF, t + 3);
;       WAIT_V(6); BAR; MMA(1, 1, At, B1); BAR;
;     }
;     { LDB(B0, 0, 0); LDA(At, 0, 0); STAGE(SA(1, 1), A, brow + HALF, nt - 1);
;       BAR; WAIT_L(0); MMA(0, 0, At, B0); BAR;
;       LDB(B1, 0, 1); BAR; WAIT_L(0); MMA(0, 1, At, B1); BAR;
	s_waitcnt lgkmcnt(0)
	s_waitcnt lgkmcnt(0)
	v_mfma_f32_16x16x32_bf16 v[62:65], v[164:167], v[148:151], v[62:65]
	v_mfma_f32_16x16x32_bf16 v[58:61], v[164:167], v[156:159], v[58:61]
	v_mfma_f32_16x16x32_bf16 v[54:57], v[188:191], v[148:151], v[54:57]
	v_mfma_f32_16x16x32_bf16 v[50:53], v[188:191], v[156:159], v[50:53]
	v_mfma_f32_16x16x32_bf16 v[46:49], v[196:199], v[148:151], v[46:49]
	v_mfma_f32_16x16x32_bf16 v[42:45], v[196:199], v[156:159], v[42:45]
	v_mfma_f32_16x16x32_bf16 v[38:41], v[204:207], v[148:151], v[38:41]
	v_mfma_f32_16x16x32_bf16 v[34:37], v[204:207], v[156:159], v[34:37]
	v_mfma_f32_16x16x32_bf16 v[62:65], v[184:187], v[152:155], v[62:65]
	v_mfma_f32_16x16x32_bf16 v[58:61], v[184:187], v[160:163], v[58:61]
	v_mfma_f32_16x16x32_bf16 v[54:57], v[192:195], v[152:155], v[54:57]
	v_mfma_f32_16x16x32_bf16 v[50:53], v[192:195], v[160:163], v[50:53]
	v_mfma_f32_16x16x32_bf16 v[46:49], v[200:203], v[152:155], v[46:49]
	v_mfma_f32_16x16x32_bf16 v[42:45], v[200:203], v[160:163], v[42:45]
	v_mfma_f32_16x16x32_bf16 v[38:41], v[208:211], v[152:155], v[38:41]
	v_mfma_f32_16x16x32_bf16 v[34:37], v[208:211], v[160:163], v[34:37]
	s_barrier
	s_add_u32 s42, s44, 0x80180
	s_addc_u32 s43, s45, 0
	s_mov_b32 m0, s20
	s_nop 0
	v_lshl_add_u64 v[148:149], s[42:43], 0, v[0:1]
	global_load_lds_dwordx4 v[148:149], off
	v_lshl_add_u64 v[148:149], s[42:43], 0, v[140:141]
	s_mov_b32 m0, s21
	s_nop 0
	global_load_lds_dwordx4 v[148:149], off
	s_waitcnt vmcnt(6)
	s_barrier
	v_mfma_f32_16x16x32_bf16 v[30:33], v[164:167], v[212:215], v[30:33]
	v_mfma_f32_16x16x32_bf16 v[26:29], v[164:167], v[220:223], v[26:29]
	v_mfma_f32_16x16x32_bf16 v[22:25], v[188:191], v[212:215], v[22:25]
	v_mfma_f32_16x16x32_bf16 v[18:21], v[188:191], v[220:223], v[18:21]
	v_mfma_f32_16x16x32_bf16 v[14:17], v[196:199], v[212:215], v[14:17]
	v_mfma_f32_16x16x32_bf16 v[10:13], v[196:199], v[220:223], v[10:13]
	v_mfma_f32_16x16x32_bf16 v[6:9], v[204:207], v[212:215], v[6:9]
	v_mfma_f32_16x16x32_bf16 v[2:5], v[204:207], v[220:223], v[2:5]
	v_mfma_f32_16x16x32_bf16 v[30:33], v[184:187], v[216:219], v[30:33]
	v_mfma_f32_16x16x32_bf16 v[26:29], v[184:187], v[224:227], v[26:29]
	v_mfma_f32_16x16x32_bf16 v[22:25], v[192:195], v[216:219], v[22:25]
	v_mfma_f32_16x16x32_bf16 v[18:21], v[192:195], v[224:227], v[18:21]
	v_mfma_f32_16x16x32_bf16 v[14:17], v[200:203], v[216:219], v[14:17]
	v_mfma_f32_16x16x32_bf16 v[10:13], v[200:203], v[224:227], v[10:13]
	v_mfma_f32_16x16x32_bf16 v[6:9], v[208:211], v[216:219], v[6:9]
	v_mfma_f32_16x16x32_bf16 v[2:5], v[208:211], v[224:227], v[2:5]
	s_add_i32 s36, s36, 2
	s_add_u32 s6, s6, 0x100
	s_addc_u32 s7, s7, 0
	s_cmp_gt_u32 s36, 27
	s_barrier
	s_cbranch_scc0 .LBB0_418
	s_add_u32 s4, s4, 0xf80
	s_addc_u32 s5, s5, 0
	s_mov_b32 m0, s41
	ds_read_b128 v[148:151], v143
	ds_read_b128 v[152:155], v143 offset:1024
	ds_read_b128 v[156:159], v143 offset:2048
	ds_read_b128 v[160:163], v143 offset:3072
	ds_read_b128 v[164:167], v133
	ds_read_b128 v[184:187], v133 offset:1024
	ds_read_b128 v[188:191], v134
	ds_read_b128 v[192:195], v134 offset:1024
	ds_read_b128 v[196:199], v137
	ds_read_b128 v[200:203], v137 offset:1024
	ds_read_b128 v[204:207], v139
	ds_read_b128 v[208:211], v139 offset:1024
	s_nop 0
	v_lshl_add_u64 v[142:143], s[4:5], 0, v[0:1]
	global_load_lds_dwordx4 v[142:143], off
	v_lshl_add_u64 v[140:141], s[4:5], 0, v[140:141]
	s_mov_b32 m0, s37
	s_nop 0
	global_load_lds_dwordx4 v[140:141], off
	s_barrier
	s_waitcnt lgkmcnt(0)
	s_setprio 1
	s_waitcnt lgkmcnt(0)
	v_mfma_f32_16x16x32_bf16 v[126:129], v[164:167], v[148:151], v[126:129]
	v_mfma_f32_16x16x32_bf16 v[122:125], v[164:167], v[156:159], v[122:125]
	v_mfma_f32_16x16x32_bf16 v[118:121], v[188:191], v[148:151], v[118:121]
	v_mfma_f32_16x16x32_bf16 v[110:113], v[196:199], v[148:151], v[110:113]
	v_mfma_f32_16x16x32_bf16 v[106:109], v[196:199], v[156:159], v[106:109]
	v_mfma_f32_16x16x32_bf16 v[102:105], v[204:207], v[148:151], v[102:105]
	v_mfma_f32_16x16x32_bf16 v[98:101], v[204:207], v[156:159], v[98:101]
	v_mfma_f32_16x16x32_bf16 v[126:129], v[184:187], v[152:155], v[126:129]
	v_mfma_f32_16x16x32_bf16 v[122:125], v[184:187], v[160:163], v[122:125]
	v_mfma_f32_16x16x32_bf16 v[118:121], v[192:195], v[152:155], v[118:121]
	v_mfma_f32_16x16x32_bf16 v[114:117], v[188:191], v[156:159], v[114:117]
	v_mfma_f32_16x16x32_bf16 v[110:113], v[200:203], v[152:155], v[110:113]
	v_mfma_f32_16x16x32_bf16 v[106:109], v[200:203], v[160:163], v[106:109]
	v_mfma_f32_16x16x32_bf16 v[102:105], v[208:211], v[152:155], v[102:105]
	v_mfma_f32_16x16x32_bf16 v[98:101], v[208:211], v[160:163], v[98:101]
	v_mfma_f32_16x16x32_bf16 v[140:143], v[192:195], v[160:163], v[114:117]
	s_setprio 0
	s_barrier
	s_nop 0
	ds_read_b128 v[114:117], v144
	ds_read_b128 v[212:215], v144 offset:1024
	ds_read_b128 v[216:219], v144 offset:2048
	ds_read_b128 v[220:223], v144 offset:3072
	s_barrier
	s_waitcnt lgkmcnt(0)
	s_setprio 1
	s_waitcnt lgkmcnt(0)
	v_mfma_f32_16x16x32_bf16 v[90:93], v[164:167], v[216:219], v[90:93]
	v_mfma_f32_16x16x32_bf16 v[86:89], v[188:191], v[114:117], v[86:89]
	v_mfma_f32_16x16x32_bf16 v[94:97], v[164:167], v[114:117], v[94:97]
	v_mfma_f32_16x16x32_bf16 v[90:93], v[184:187], v[220:223], v[90:93]
	v_mfma_f32_16x16x32_bf16 v[86:89], v[192:195], v[212:215], v[86:89]
	v_mfma_f32_16x16x32_bf16 v[82:85], v[188:191], v[216:219], v[82:85]
	v_mfma_f32_16x16x32_bf16 v[78:81], v[196:199], v[114:117], v[78:81]
	v_mfma_f32_16x16x32_bf16 v[74:77], v[196:199], v[216:219], v[74:77]
	v_mfma_f32_16x16x32_bf16 v[70:73], v[204:207], v[114:117], v[70:73]
	v_mfma_f32_16x16x32_bf16 v[66:69], v[204:207], v[216:219], v[66:69]
	v_mfma_f32_16x16x32_bf16 v[224:227], v[184:187], v[212:215], v[94:97]
	v_mfma_f32_16x16x32_bf16 v[164:167], v[192:195], v[220:223], v[82:85]
	v_mfma_f32_16x16x32_bf16 v[184:187], v[200:203], v[212:215], v[78:81]
	v_mfma_f32_16x16x32_bf16 v[188:191], v[200:203], v[220:223], v[74:77]
	v_mfma_f32_16x16x32_bf16 v[192:195], v[208:211], v[212:215], v[70:73]
	v_mfma_f32_16x16x32_bf16 v[196:199], v[208:211], v[220:223], v[66:69]
	s_setprio 0
	s_barrier
; #define LDA(dst, b, h) for (int m = 0; m < 4; ++m) for (int k = 0; k < 2; ++k) \
;     dst[m][k] = *reinterpret_cast<const bf16x8*>((char*)SA(b, h) + lds_byte(wr * 64 + m * 16 + fr, k * 32 + fq * 8))
; #define LDB(dst, b, h) for (int n = 0; n < 2; ++n) for (int k = 0; k < 2; ++k) \
;     dst[n][k] = *reinterpret_cast<const bf16x8*>((char*)SB(b, h) + lds_byte(wc * 32 + n * 16 + fr, k * 32 + fq * 8))
; #define MMA(ai, bj, At, Bt_) do { __builtin_amdgcn_s_setprio(1); \
;     for (int m = 0; m < 4; ++m) for (int n = 0; n < 2; ++n) for (int k = 0; k < 2; ++k) \
;       acc[ai][bj][m][n] = __builtin_amdgcn_mfma_f32_16x16x32_bf16(At[m][k], Bt_[n][k], acc[ai][bj][m][n], 0, 0, 0); \
;     __builtin_amdgcn_s_setprio(0); } while (0)
; #define WAIT_V(n) asm volatile("s_waitcnt vmcnt(" #n ")" ::: "memory")
; #define WAIT_L(n) asm volatile("s_waitcnt lgkmcnt(" #n ")" ::: "memory")
; #define BAR __builtin_amdgcn_s_barrier()
;     ...
;       LDA(At, 0, 1); WAIT_V(4); BAR; WAIT_L(0); MMA(1, 0, At, B0); MMA(1, 1, At, B1); BAR; }
;     { LDB(B0, 1, 0); LDA(At, 1, 0); WAIT_V(2); BAR; WAIT_L(0); MMA(0, 0, At, B0); BAR;
	s_nop 0
	ds_read_b128 v[66:69], v133 offset:16384
	ds_read_b128 v[70:73], v133 offset:17408
	ds_read_b128 v[74:77], v134 offset:16384
	ds_read_b128 v[78:81], v134 offset:17408
	ds_read_b128 v[82:85], v137 offset:16384
	ds_read_b128 v[94:97], v137 offset:17408
	ds_read_b128 v[200:203], v139 offset:16384
	ds_read_b128 v[204:207], v139 offset:17408
	s_waitcnt vmcnt(4)
	s_barrier
	s_waitcnt lgkmcnt(0)
	s_setprio 1
	s_waitcnt lgkmcnt(0)
	v_mfma_f32_16x16x32_bf16 v[62:65], v[66:69], v[148:151], v[62:65]
	v_mfma_f32_16x16x32_bf16 v[58:61], v[66:69], v[156:159], v[58:61]
	v_mfma_f32_16x16x32_bf16 v[54:57], v[74:77], v[148:151], v[54:57]
	v_mfma_f32_16x16x32_bf16 v[50:53], v[74:77], v[156:159], v[50:53]
	v_mfma_f32_16x16x32_bf16 v[46:49], v[82:85], v[148:151], v[46:49]
	v_mfma_f32_16x16x32_bf16 v[42:45], v[82:85], v[156:159], v[42:45]
	v_mfma_f32_16x16x32_bf16 v[38:41], v[200:203], v[148:151], v[38:41]
	v_mfma_f32_16x16x32_bf16 v[34:37], v[200:203], v[156:159], v[34:37]
	v_mfma_f32_16x16x32_bf16 v[62:65], v[70:73], v[152:155], v[62:65]
	v_mfma_f32_16x16x32_bf16 v[58:61], v[70:73], v[160:163], v[58:61]
	v_mfma_f32_16x16x32_bf16 v[54:57], v[78:81], v[152:155], v[54:57]
	v_mfma_f32_16x16x32_bf16 v[50:53], v[78:81], v[160:163], v[50:53]
	v_mfma_f32_16x16x32_bf16 v[46:49], v[94:97], v[152:155], v[46:49]
	v_mfma_f32_16x16x32_bf16 v[42:45], v[94:97], v[160:163], v[42:45]
	v_mfma_f32_16x16x32_bf16 v[38:41], v[204:207], v[152:155], v[38:41]
	v_mfma_f32_16x16x32_bf16 v[34:37], v[204:207], v[160:163], v[34:37]
	s_setprio 0
	s_setprio 1
	v_mfma_f32_16x16x32_bf16 v[30:33], v[66:69], v[114:117], v[30:33]
	v_mfma_f32_16x16x32_bf16 v[26:29], v[66:69], v[216:219], v[26:29]
	v_mfma_f32_16x16x32_bf16 v[22:25], v[74:77], v[114:117], v[22:25]
	v_mfma_f32_16x16x32_bf16 v[18:21], v[74:77], v[216:219], v[18:21]
	v_mfma_f32_16x16x32_bf16 v[14:17], v[82:85], v[114:117], v[14:17]
	v_mfma_f32_16x16x32_bf16 v[10:13], v[82:85], v[216:219], v[10:13]
	v_mfma_f32_16x16x32_bf16 v[6:9], v[200:203], v[114:117], v[6:9]
	v_mfma_f32_16x16x32_bf16 v[2:5], v[200:203], v[216:219], v[2:5]
	v_mfma_f32_16x16x32_bf16 v[148:151], v[70:73], v[212:215], v[30:33]
	v_mfma_f32_16x16x32_bf16 v[152:155], v[70:73], v[220:223], v[26:29]
	v_mfma_f32_16x16x32_bf16 v[156:159], v[78:81], v[212:215], v[22:25]
	v_mfma_f32_16x16x32_bf16 v[160:163], v[78:81], v[220:223], v[18:21]
	v_mfma_f32_16x16x32_bf16 v[208:211], v[94:97], v[212:215], v[14:17]
	v_mfma_f32_16x16x32_bf16 v[228:231], v[94:97], v[220:223], v[10:13]
	v_mfma_f32_16x16x32_bf16 v[212:215], v[204:207], v[212:215], v[6:9]
	v_mfma_f32_16x16x32_bf16 v[200:203], v[204:207], v[220:223], v[2:5]
	s_setprio 0
	s_barrier
	ds_read_b128 v[14:17], v145
	ds_read_b128 v[30:33], v145 offset:1024
	ds_read_b128 v[204:207], v145 offset:2048
	ds_read_b128 v[216:219], v145 offset:3072
	ds_read_b128 v[2:5], v133 offset:32768
	ds_read_b128 v[6:9], v133 offset:33792
	ds_read_b128 v[10:13], v134 offset:32768
	ds_read_b128 v[18:21], v134 offset:33792
	ds_read_b128 v[22:25], v137 offset:32768
	ds_read_b128 v[26:29], v137 offset:33792
	ds_read_b128 v[220:223], v139 offset:32768
	ds_read_b128 v[232:235], v139 offset:33792
	s_waitcnt vmcnt(2)
	s_barrier
	s_waitcnt lgkmcnt(0)
	s_setprio 1
	s_waitcnt lgkmcnt(0)
	v_mfma_f32_16x16x32_bf16 v[66:69], v[2:5], v[14:17], v[126:129]
	v_mfma_f32_16x16x32_bf16 v[114:117], v[6:9], v[30:33], v[66:69]
	v_mfma_f32_16x16x32_bf16 v[66:69], v[2:5], v[204:207], v[122:125]
	v_mfma_f32_16x16x32_bf16 v[126:129], v[6:9], v[216:219], v[66:69]
	v_mfma_f32_16x16x32_bf16 v[66:69], v[10:13], v[14:17], v[118:121]
	v_mfma_f32_16x16x32_bf16 v[82:85], v[18:21], v[30:33], v[66:69]
	v_mfma_f32_16x16x32_bf16 v[66:69], v[10:13], v[204:207], v[140:143]
	v_mfma_f32_16x16x32_bf16 v[94:97], v[18:21], v[216:219], v[66:69]
	v_mfma_f32_16x16x32_bf16 v[66:69], v[22:25], v[14:17], v[110:113]
	v_mfma_f32_16x16x32_bf16 v[74:77], v[26:29], v[30:33], v[66:69]
	v_mfma_f32_16x16x32_bf16 v[66:69], v[22:25], v[204:207], v[106:109]
	v_mfma_f32_16x16x32_bf16 v[78:81], v[26:29], v[216:219], v[66:69]
	v_mfma_f32_16x16x32_bf16 v[66:69], v[220:223], v[14:17], v[102:105]
	v_mfma_f32_16x16x32_bf16 v[70:73], v[220:223], v[204:207], v[98:101]
	v_mfma_f32_16x16x32_bf16 v[66:69], v[232:235], v[30:33], v[66:69]
	v_mfma_f32_16x16x32_bf16 v[70:73], v[232:235], v[216:219], v[70:73]
	s_setprio 0
	s_barrier
; #define LDA(dst, b, h) for (int m = 0; m < 4; ++m) for (int k = 0; k < 2; ++k) \
;     dst[m][k] = *reinterpret_cast<const bf16x8*>((char*)SA(b, h) + lds_byte(wr * 64 + m * 16 + fr, k * 32 + fq * 8))
; #define LDB(dst, b, h) for (int n = 0; n < 2; ++n) for (int k = 0; k < 2; ++k) \
;     dst[n][k] = *reinterpret_cast<const bf16x8*>((char*)SB(b, h) + lds_byte(wc * 32 + n * 16 + fr, k * 32 + fq * 8))
; #define MMA(ai, bj, At, Bt_) do { __builtin_amdgcn_s_setprio(1); \
;     for (int m = 0; m < 4; ++m) for (int n = 0; n < 2; ++n) for (int k = 0; k < 2; ++k) \
;       acc[ai][bj][m][n] = __builtin_amdgcn_mfma_f32_16x16x32_bf16(At[m][k], Bt_[n][k], acc[ai][bj][m][n], 0, 0, 0); \
;     __builtin_amdgcn_s_setprio(0); } while (0)
; #define WAIT_V(n) asm volatile("s_waitcnt vmcnt(" #n ")" ::: "memory")
; #define WAIT_L(n) asm volatile("s_waitcnt lgkmcnt(" #n ")" ::: "memory")
; #define BAR __builtin_amdgcn_s_barrier()
;     ...
;       LDB(B1, 1, 1); WAIT_V(0); BAR; WAIT_L(0); MMA(0, 1, At, B1); BAR;
;       LDA(At, 1, 1); BAR; WAIT_L(0); MMA(1, 0, At, B0); MMA(1, 1, At, B1); BAR; }
;     if (wr == 0) BAR;
	ds_read_b128 v[140:143], v146
	ds_read_b128 v[236:239], v146 offset:1024
	ds_read_b128 v[240:243], v146 offset:2048
	ds_read_b128 v[144:147], v146 offset:3072
	s_waitcnt vmcnt(0)
	s_barrier
	s_waitcnt lgkmcnt(0)
	s_setprio 1
	s_waitcnt lgkmcnt(0)
	v_mfma_f32_16x16x32_bf16 v[98:101], v[2:5], v[140:143], v[224:227]
	v_mfma_f32_16x16x32_bf16 v[2:5], v[2:5], v[240:243], v[90:93]
	v_mfma_f32_16x16x32_bf16 v[118:121], v[6:9], v[144:147], v[2:5]
	v_mfma_f32_16x16x32_bf16 v[2:5], v[10:13], v[140:143], v[86:89]
	v_mfma_f32_16x16x32_bf16 v[102:105], v[18:21], v[236:239], v[2:5]
	v_mfma_f32_16x16x32_bf16 v[2:5], v[10:13], v[240:243], v[164:167]
	v_mfma_f32_16x16x32_bf16 v[122:125], v[18:21], v[144:147], v[2:5]
	v_mfma_f32_16x16x32_bf16 v[2:5], v[22:25], v[140:143], v[184:187]
	v_mfma_f32_16x16x32_bf16 v[90:93], v[26:29], v[236:239], v[2:5]
	v_mfma_f32_16x16x32_bf16 v[2:5], v[22:25], v[240:243], v[188:191]
	v_mfma_f32_16x16x32_bf16 v[110:113], v[26:29], v[144:147], v[2:5]
	v_mfma_f32_16x16x32_bf16 v[2:5], v[220:223], v[140:143], v[192:195]
	v_mfma_f32_16x16x32_bf16 v[86:89], v[232:235], v[236:239], v[2:5]
	v_mfma_f32_16x16x32_bf16 v[2:5], v[220:223], v[240:243], v[196:199]
	v_mfma_f32_16x16x32_bf16 v[98:101], v[6:9], v[236:239], v[98:101]
	v_mfma_f32_16x16x32_bf16 v[106:109], v[232:235], v[144:147], v[2:5]
	s_setprio 0
	s_barrier
	ds_read_b128 v[164:167], v133 offset:49152
	ds_read_b128 v[184:187], v133 offset:50176
	ds_read_b128 v[188:191], v134 offset:49152
	ds_read_b128 v[192:195], v134 offset:50176
	ds_read_b128 v[196:199], v137 offset:49152
	ds_read_b128 v[220:223], v137 offset:50176
	ds_read_b128 v[224:227], v139 offset:49152
	ds_read_b128 v[232:235], v139 offset:50176
	s_barrier
	s_waitcnt lgkmcnt(0)
	s_setprio 1
	s_waitcnt lgkmcnt(0)
	v_mfma_f32_16x16x32_bf16 v[6:9], v[164:167], v[204:207], v[58:61]
	v_mfma_f32_16x16x32_bf16 v[10:13], v[188:191], v[204:207], v[50:53]
	v_mfma_f32_16x16x32_bf16 v[2:5], v[164:167], v[14:17], v[62:65]
	v_mfma_f32_16x16x32_bf16 v[18:21], v[184:187], v[216:219], v[6:9]
	v_mfma_f32_16x16x32_bf16 v[6:9], v[188:191], v[14:17], v[54:57]
	v_mfma_f32_16x16x32_bf16 v[22:25], v[192:195], v[216:219], v[10:13]
	v_mfma_f32_16x16x32_bf16 v[10:13], v[196:199], v[14:17], v[46:49]
	v_mfma_f32_16x16x32_bf16 v[14:17], v[224:227], v[14:17], v[38:41]
	v_mfma_f32_16x16x32_bf16 v[2:5], v[184:187], v[30:33], v[2:5]
	v_mfma_f32_16x16x32_bf16 v[6:9], v[192:195], v[30:33], v[6:9]
	v_mfma_f32_16x16x32_bf16 v[10:13], v[220:223], v[30:33], v[10:13]
	v_mfma_f32_16x16x32_bf16 v[26:29], v[196:199], v[204:207], v[42:45]
	v_mfma_f32_16x16x32_bf16 v[14:17], v[232:235], v[30:33], v[14:17]
	v_mfma_f32_16x16x32_bf16 v[30:33], v[224:227], v[204:207], v[34:37]
	v_mfma_f32_16x16x32_bf16 v[26:29], v[220:223], v[216:219], v[26:29]
	v_mfma_f32_16x16x32_bf16 v[30:33], v[232:235], v[216:219], v[30:33]
	s_setprio 0
	s_setprio 1
	v_mfma_f32_16x16x32_bf16 v[38:41], v[164:167], v[240:243], v[152:155]
	v_mfma_f32_16x16x32_bf16 v[42:45], v[188:191], v[240:243], v[160:163]
	v_mfma_f32_16x16x32_bf16 v[46:49], v[196:199], v[240:243], v[228:231]
	v_mfma_f32_16x16x32_bf16 v[34:37], v[164:167], v[140:143], v[148:151]
	v_mfma_f32_16x16x32_bf16 v[50:53], v[184:187], v[144:147], v[38:41]
	v_mfma_f32_16x16x32_bf16 v[38:41], v[188:191], v[140:143], v[156:159]
	v_mfma_f32_16x16x32_bf16 v[54:57], v[192:195], v[144:147], v[42:45]
	v_mfma_f32_16x16x32_bf16 v[42:45], v[196:199], v[140:143], v[208:211]
	v_mfma_f32_16x16x32_bf16 v[58:61], v[220:223], v[144:147], v[46:49]
	v_mfma_f32_16x16x32_bf16 v[46:49], v[224:227], v[140:143], v[212:215]
	v_mfma_f32_16x16x32_bf16 v[62:65], v[224:227], v[240:243], v[200:203]
	v_mfma_f32_16x16x32_bf16 v[34:37], v[184:187], v[236:239], v[34:37]
	v_mfma_f32_16x16x32_bf16 v[38:41], v[192:195], v[236:239], v[38:41]
	v_mfma_f32_16x16x32_bf16 v[42:45], v[220:223], v[236:239], v[42:45]
	v_mfma_f32_16x16x32_bf16 v[46:49], v[232:235], v[236:239], v[46:49]
	v_mfma_f32_16x16x32_bf16 v[62:65], v[232:235], v[144:147], v[62:65]
	s_setprio 0
	v_readlane_b32 s4, v245, 33
	v_readlane_b32 s5, v245, 34
	s_and_b64 vcc, exec, s[4:5]
	s_barrier
	s_cbranch_vccz .LBB0_421
	s_barrier
